# combine loop batched + prologue transpose readback with all 32 ds_read2 in flight (no pool change)
# baseline (speedup 1.0000x reference)
; #define LAS __attribute__((address_space(3)))
; __device__ __forceinline__ unsigned pk2(float lo, float hi) { return pg8::cvt_pk_bf16(lo, hi); }
; __device__ __forceinline__ void p0_transpose_item(const float* __restrict__ W, const float* __restrict__ gain, int K, int N, bf16* __restrict__ WT, int mode, LAS float* scr, int item, int lane) {
;     ...
;     for (int i = 0; i < 16; ++i) { LAS float* d = scr + (4 * i + lr) * 65 + lc4; d[0] = v[i].x; d[1] = v[i].y; d[2] = v[i].z; d[3] = v[i].w; }
;     asm volatile("s_waitcnt lgkmcnt(0)" ::: "memory");
;     const int c = lane & 7;
;     const int rowbase = mode == 0 ? n0 : (((n0 >> 7) << 8) + (n0 & 127) + (mode == 2 ? 128 : 0));
; #pragma unroll
;     for (int j = 0; j < 8; ++j) { const int n = (lane >> 3) + 8 * j; const LAS float* s = scr + (8 * c) * 65 + n;
;         v4u o; o.x = pk2(s[0 * 65], s[1 * 65]); o.y = pk2(s[2 * 65], s[3 * 65]); o.z = pk2(s[4 * 65], s[5 * 65]); o.w = pk2(s[6 * 65], s[7 * 65]);
;         *(v4u*)(WT + (size_t)(rowbase + n) * K + k0 + 8 * c) = o; }
;     asm volatile("s_waitcnt lgkmcnt(0)" ::: "memory");
.LBB0_2:
	s_waitcnt vmcnt(15)
	ds_write2_b32 v73, v6, v7 offset1:1
	ds_write2_b32 v73, v8, v9 offset0:2 offset1:3
	s_waitcnt vmcnt(14)
	ds_write2_b32 v83, v2, v3 offset1:1
	ds_write2_b32 v84, v4, v5 offset1:1
	s_waitcnt vmcnt(13)
	ds_write2_b32 v85, v14, v15 offset1:1
	ds_write2_b32 v86, v16, v17 offset1:1
	s_waitcnt vmcnt(12)
	ds_write2_b32 v87, v10, v11 offset1:1
	ds_write2_b32 v88, v12, v13 offset1:1
	s_waitcnt vmcnt(11)
	ds_write2_b32 v89, v22, v23 offset1:1
	ds_write2_b32 v90, v24, v25 offset1:1
	s_waitcnt vmcnt(10)
	ds_write2_b32 v91, v18, v19 offset1:1
	ds_write2_b32 v92, v20, v21 offset1:1
	s_waitcnt vmcnt(9)
	ds_write2_b32 v93, v30, v31 offset1:1
	ds_write2_b32 v94, v32, v33 offset1:1
	s_waitcnt vmcnt(8)
	ds_write2_b32 v95, v26, v27 offset1:1
	ds_write2_b32 v96, v28, v29 offset1:1
	s_waitcnt vmcnt(7)
	ds_write2_b32 v97, v38, v39 offset1:1
	ds_write2_b32 v98, v40, v41 offset1:1
	s_waitcnt vmcnt(6)
	ds_write2_b32 v99, v34, v35 offset1:1
	ds_write2_b32 v100, v36, v37 offset1:1
	s_waitcnt vmcnt(5)
	ds_write2_b32 v101, v62, v63 offset1:1
	ds_write2_b32 v102, v64, v65 offset1:1
	s_waitcnt vmcnt(4)
	ds_write2_b32 v103, v58, v59 offset1:1
	ds_write2_b32 v104, v60, v61 offset1:1
	s_waitcnt vmcnt(3)
	ds_write2_b32 v105, v54, v55 offset1:1
	ds_write2_b32 v106, v56, v57 offset1:1
	s_waitcnt vmcnt(2)
	ds_write2_b32 v107, v50, v51 offset1:1
	ds_write2_b32 v108, v52, v53 offset1:1
	s_waitcnt vmcnt(1)
	ds_write2_b32 v109, v46, v47 offset1:1
	ds_write2_b32 v110, v48, v49 offset1:1
	s_waitcnt vmcnt(0)
	ds_write2_b32 v111, v42, v43 offset1:1
	ds_write2_b32 v112, v44, v45 offset1:1
	s_waitcnt lgkmcnt(0)
	ds_read2_b32 v[150:151], v75 offset1:65
	ds_read2_b32 v[152:153], v75 offset0:130 offset1:195
	ds_read2_b32 v[154:155], v113 offset0:4 offset1:69
	ds_read2_b32 v[156:157], v113 offset0:134 offset1:199
	ds_read2_b32 v[158:159], v75 offset0:8 offset1:73
	ds_read2_b32 v[160:161], v75 offset0:138 offset1:203
	ds_read2_b32 v[162:163], v113 offset0:12 offset1:77
	ds_read2_b32 v[164:165], v113 offset0:142 offset1:207
	ds_read2_b32 v[166:167], v75 offset0:16 offset1:81
	ds_read2_b32 v[168:169], v75 offset0:146 offset1:211
	ds_read2_b32 v[170:171], v113 offset0:20 offset1:85
	ds_read2_b32 v[172:173], v113 offset0:150 offset1:215
	ds_read2_b32 v[174:175], v75 offset0:24 offset1:89
	ds_read2_b32 v[176:177], v75 offset0:154 offset1:219
	ds_read2_b32 v[178:179], v113 offset0:28 offset1:93
	ds_read2_b32 v[180:181], v113 offset0:158 offset1:223
	ds_read2_b32 v[182:183], v75 offset0:32 offset1:97
	ds_read2_b32 v[184:185], v75 offset0:162 offset1:227
	ds_read2_b32 v[186:187], v113 offset0:36 offset1:101
	ds_read2_b32 v[188:189], v113 offset0:166 offset1:231
	ds_read2_b32 v[190:191], v75 offset0:40 offset1:105
	ds_read2_b32 v[192:193], v75 offset0:170 offset1:235
	ds_read2_b32 v[194:195], v113 offset0:44 offset1:109
	ds_read2_b32 v[196:197], v113 offset0:174 offset1:239
	ds_read2_b32 v[198:199], v75 offset0:48 offset1:113
	ds_read2_b32 v[200:201], v75 offset0:178 offset1:243
	ds_read2_b32 v[202:203], v113 offset0:52 offset1:117
	ds_read2_b32 v[204:205], v113 offset0:182 offset1:247
	ds_read2_b32 v[206:207], v75 offset0:56 offset1:121
	ds_read2_b32 v[208:209], v75 offset0:186 offset1:251
	ds_read2_b32 v[210:211], v113 offset0:60 offset1:125
	ds_read2_b32 v[212:213], v113 offset0:190 offset1:255
	s_waitcnt lgkmcnt(15)
	v_cvt_pk_bf16_f32 v214, v150, v151
	s_lshl_b32 s20, s21, 7
	s_and_b32 s20, s20, 0xffffff00
	s_waitcnt lgkmcnt(15)
	v_cvt_pk_bf16_f32 v215, v152, v153
	s_and_b32 s21, s24, 64
	s_ashr_i32 s23, s22, 31
	s_or_b32 s20, s21, s20
	s_lshl_b64 s[22:23], s[22:23], 1
	s_waitcnt lgkmcnt(15)
	v_cvt_pk_bf16_f32 v216, v154, v155
	s_add_u32 s22, s52, s22
	s_waitcnt lgkmcnt(15)
; #define LAS __attribute__((address_space(3)))
; __device__ __forceinline__ unsigned pk2(float lo, float hi) { return pg8::cvt_pk_bf16(lo, hi); }
; __device__ __forceinline__ void p0_transpose_item(const float* __restrict__ W, const float* __restrict__ gain, int K, int N, bf16* __restrict__ WT, int mode, LAS float* scr, int item, int lane) {
;     ...
;     for (int j = 0; j < 8; ++j) { const int n = (lane >> 3) + 8 * j; const LAS float* s = scr + (8 * c) * 65 + n;
;         v4u o; o.x = pk2(s[0 * 65], s[1 * 65]); o.y = pk2(s[2 * 65], s[3 * 65]); o.z = pk2(s[4 * 65], s[5 * 65]); o.w = pk2(s[6 * 65], s[7 * 65]);
;         *(v4u*)(WT + (size_t)(rowbase + n) * K + k0 + 8 * c) = o; }
;     asm volatile("s_waitcnt lgkmcnt(0)" ::: "memory");
	v_cvt_pk_bf16_f32 v217, v156, v157
	v_or_b32_e32 v6, s20, v74
	s_addc_u32 s23, s53, s23
	v_mov_b32_e32 v69, v67
	v_ashrrev_i32_e32 v7, 31, v6
	v_lshl_add_u64 v[8:9], s[22:23], 0, v[68:69]
	v_lshlrev_b64 v[6:7], 12, v[6:7]
	v_lshl_add_u64 v[6:7], v[8:9], 0, v[6:7]
	global_store_dwordx4 v[6:7], v[214:217], off
	v_readlane_b32 s76, v254, 21
	v_readlane_b32 s77, v254, 22
	s_waitcnt lgkmcnt(15)
	v_cvt_pk_bf16_f32 v218, v158, v159
	s_waitcnt lgkmcnt(15)
	v_cvt_pk_bf16_f32 v219, v160, v161
	s_waitcnt lgkmcnt(15)
	v_cvt_pk_bf16_f32 v220, v162, v163
	s_waitcnt lgkmcnt(15)
	v_cvt_pk_bf16_f32 v221, v164, v165
	v_or_b32_e32 v6, s20, v76
	v_ashrrev_i32_e32 v7, 31, v6
	v_lshlrev_b64 v[6:7], 12, v[6:7]
	v_lshl_add_u64 v[6:7], v[8:9], 0, v[6:7]
	global_store_dwordx4 v[6:7], v[218:221], off
	v_readlane_b32 s78, v254, 23
	v_readlane_b32 s79, v254, 24
	s_waitcnt lgkmcnt(15)
	v_cvt_pk_bf16_f32 v222, v166, v167
	s_waitcnt lgkmcnt(15)
	v_cvt_pk_bf16_f32 v223, v168, v169
	s_waitcnt lgkmcnt(15)
	v_cvt_pk_bf16_f32 v224, v170, v171
	s_waitcnt lgkmcnt(15)
	v_cvt_pk_bf16_f32 v225, v172, v173
	v_or_b32_e32 v6, s20, v77
	v_ashrrev_i32_e32 v7, 31, v6
	v_lshlrev_b64 v[6:7], 12, v[6:7]
	v_lshl_add_u64 v[6:7], v[8:9], 0, v[6:7]
	global_store_dwordx4 v[6:7], v[222:225], off
	v_readlane_b32 s80, v254, 25
	v_readlane_b32 s81, v254, 26
	s_waitcnt lgkmcnt(15)
	v_cvt_pk_bf16_f32 v226, v174, v175
	s_waitcnt lgkmcnt(15)
	v_cvt_pk_bf16_f32 v227, v176, v177
	s_waitcnt lgkmcnt(15)
	v_cvt_pk_bf16_f32 v228, v178, v179
	s_waitcnt lgkmcnt(15)
	v_cvt_pk_bf16_f32 v229, v180, v181
	v_or_b32_e32 v6, s20, v78
	v_ashrrev_i32_e32 v7, 31, v6
	v_lshlrev_b64 v[6:7], 12, v[6:7]
	v_lshl_add_u64 v[6:7], v[8:9], 0, v[6:7]
	global_store_dwordx4 v[6:7], v[226:229], off
	v_readlane_b32 s82, v254, 27
	v_readlane_b32 s83, v254, 28
	s_waitcnt lgkmcnt(15)
	v_cvt_pk_bf16_f32 v230, v182, v183
	s_waitcnt lgkmcnt(14)
	v_cvt_pk_bf16_f32 v231, v184, v185
	s_waitcnt lgkmcnt(13)
	v_cvt_pk_bf16_f32 v232, v186, v187
	s_waitcnt lgkmcnt(12)
	v_cvt_pk_bf16_f32 v233, v188, v189
	v_or_b32_e32 v6, s20, v79
	v_ashrrev_i32_e32 v7, 31, v6
	v_lshlrev_b64 v[6:7], 12, v[6:7]
	v_lshl_add_u64 v[6:7], v[8:9], 0, v[6:7]
	global_store_dwordx4 v[6:7], v[230:233], off
	v_readlane_b32 s84, v254, 29
	v_readlane_b32 s85, v254, 30
	s_waitcnt lgkmcnt(11)
	v_cvt_pk_bf16_f32 v234, v190, v191
	v_or_b32_e32 v10, s20, v80
	v_ashrrev_i32_e32 v11, 31, v10
	v_lshlrev_b64 v[10:11], 12, v[10:11]
	s_waitcnt lgkmcnt(10)
	v_cvt_pk_bf16_f32 v235, v192, v193
	v_lshl_add_u64 v[10:11], v[8:9], 0, v[10:11]
	s_waitcnt lgkmcnt(9)
	v_cvt_pk_bf16_f32 v236, v194, v195
	s_waitcnt lgkmcnt(8)
	v_cvt_pk_bf16_f32 v237, v196, v197
	global_store_dwordx4 v[10:11], v[234:237], off
	v_or_b32_e32 v10, s20, v81
	s_waitcnt lgkmcnt(7)
	v_cvt_pk_bf16_f32 v238, v198, v199
	v_ashrrev_i32_e32 v11, 31, v10
	s_waitcnt lgkmcnt(6)
	v_cvt_pk_bf16_f32 v239, v200, v201
	v_lshlrev_b64 v[10:11], 12, v[10:11]
	s_waitcnt lgkmcnt(5)
	v_cvt_pk_bf16_f32 v240, v202, v203
	s_waitcnt lgkmcnt(4)
	v_cvt_pk_bf16_f32 v241, v204, v205
	v_lshl_add_u64 v[10:11], v[8:9], 0, v[10:11]
	global_store_dwordx4 v[10:11], v[238:241], off
	v_or_b32_e32 v10, s20, v82
	v_ashrrev_i32_e32 v11, 31, v10
	s_waitcnt lgkmcnt(3)
	v_cvt_pk_bf16_f32 v242, v206, v207
	s_waitcnt lgkmcnt(2)
	v_cvt_pk_bf16_f32 v243, v208, v209
	s_waitcnt lgkmcnt(1)
	v_cvt_pk_bf16_f32 v244, v210, v211
	v_lshlrev_b64 v[10:11], 12, v[10:11]
	s_waitcnt lgkmcnt(0)
	v_cvt_pk_bf16_f32 v245, v212, v213
	v_lshl_add_u64 v[6:7], v[8:9], 0, v[10:11]
	global_store_dwordx4 v[6:7], v[242:245], off
	s_waitcnt lgkmcnt(0)
	v_readlane_b32 s86, v254, 31
	v_readlane_b32 s87, v254, 32
	v_readlane_b32 s88, v254, 33
	v_readlane_b32 s89, v254, 34
	v_readlane_b32 s90, v254, 35
	v_readlane_b32 s91, v254, 36

; #define LAS __attribute__((address_space(3)))
; __device__ __forceinline__ void p0_transpose_item(const float* __restrict__ W, const float* __restrict__ gain, int K, int N, bf16* __restrict__ WT, int mode, LAS float* scr, int item, int lane) {
;     const int nblk = N / 64, kb = item / nblk, nb = item % nblk, k0 = 64 * kb, n0 = 64 * nb, lr = lane >> 4, lc4 = (lane & 15) * 4;
;     f32x4 v[16];
; #pragma unroll
;     for (int i = 0; i < 16; ++i) v[i] = *(const f32x4*)(W + (size_t)(k0 + 4 * i + lr) * N + n0 + lc4);
;     if (gain) {
; #pragma unroll
;         for (int i = 0; i < 16; ++i) v[i] = v[i] * gain[k0 + 4 * i + lr]; }
; #pragma unroll
;     for (int i = 0; i < 16; ++i) { LAS float* d = scr + (4 * i + lr) * 65 + lc4; d[0] = v[i].x; d[1] = v[i].y; d[2] = v[i].z; d[3] = v[i].w; }
;     asm volatile("s_waitcnt lgkmcnt(0)" ::: "memory");
; __device__ __forceinline__ void p0_prologue(const Args& a, LAS unsigned char* lds, int gw, int NGW, int lane, int wave) {
;     ...
;     for (int it = gw; it < DEPTH * PER_LAYER; it += NGW) {
;         const int l = it / PER_LAYER; int r = it % PER_LAYER;
;         unsigned char* wl = ws + WS_W + (size_t)l * W_LAYER;
;         const size_t og = (size_t)l * DM * DFF;
;         if (r < I_A) { p0_transpose_item(a.in[2] + og, a.in[1] + l * DM, DM, DFF, (bf16*)(wl + W_GU1), 1, scr, r, lane); continue; } r -= I_A;
;         if (r < I_A) { p0_transpose_item(a.in[3] + og, a.in[1] + l * DM, DM, DFF, (bf16*)(wl + W_GU1), 2, scr, r, lane); continue; } r -= I_A;
;         if (r < I_D) { p0_transpose_item(a.in[4] + og, nullptr, DFF, DM, (bf16*)(wl + W_D1), 0, scr, r, lane); continue; } r -= I_D;
;         if (r < I_IN) { p0_transpose_item(a.in[6] + (size_t)l * DM * DIN, a.in[5] + l * DM, DM, DIN, (bf16*)(wl + W_IN), 0, scr, r, lane); continue; } r -= I_IN;
;         if (r < I_OUT) { p0_transpose_item(a.in[10] + (size_t)l * DM * DM, nullptr, DM, DM, (bf16*)(wl + W_OUT), 0, scr, r, lane); continue; } r -= I_OUT;
;         if (r < I_A) { p0_transpose_item(a.in[12] + og, a.in[11] + l * DM, DM, DFF, (bf16*)(wl + W_GU2), 1, scr, r, lane); continue; } r -= I_A;
;         if (r < I_A) { p0_transpose_item(a.in[13] + og, a.in[11] + l * DM, DM, DFF, (bf16*)(wl + W_GU2), 2, scr, r, lane); continue; } r -= I_A;
;         p0_transpose_item(a.in[14] + og, nullptr, DFF, DM, (bf16*)(wl + W_D2), 0, scr, r, lane);
.LBB0_4:
	s_mul_hi_i32 s20, s51, 0x66666667
	s_lshr_b32 s21, s20, 31
	s_ashr_i32 s20, s20, 13
	s_add_i32 s20, s20, s21
	s_mul_i32 s21, s20, 0xffffb000
	s_add_i32 s54, s51, s21
	s_ashr_i32 s21, s20, 31
	s_mul_i32 s23, s20, 0xa000000
	s_mul_hi_i32 s22, s20, 0xa000000
	s_add_u32 s52, s5, s23
	s_addc_u32 s53, s28, s22
	s_mul_hi_i32 s23, s20, 0xb00000
	s_mul_i32 s22, s20, 0xb00000
	s_cmpk_gt_i32 s54, 0xaff
	s_mov_b64 s[24:25], -1
	s_cbranch_scc0 .LBB0_38
	s_cmpk_gt_u32 s54, 0x15ff
	s_cbranch_scc0 .LBB0_33
	s_cmpk_gt_u32 s54, 0x20ff
	s_cbranch_scc0 .LBB0_30
	s_cmpk_gt_u32 s54, 0x2aff
	s_cbranch_scc0 .LBB0_25
	s_cmpk_gt_u32 s54, 0x2eff
	s_cbranch_scc0 .LBB0_22
	s_cmpk_gt_u32 s54, 0x39ff
	s_cbranch_scc0 .LBB0_17
	s_cmpk_gt_u32 s54, 0x44ff
	s_cbranch_scc0 .LBB0_12
	s_lshl_b64 s[24:25], s[22:23], 2
	s_add_u32 s55, s88, s24
	s_mul_i32 s24, s20, 0xffff6000
	s_addc_u32 s25, s89, s25
	s_add_i32 s24, s31, s24
	s_addk_i32 s24, 0xa200
	s_and_b32 s58, s24, 0x1ffc0
	s_and_b32 s24, s29, 0x7c0
	s_lshl_b32 s56, s24, 2
	s_add_u32 s56, s55, s56
	v_or_b32_e32 v4, s58, v72
	s_addc_u32 s57, s25, 0
	v_lshl_add_u64 v[2:3], s[56:57], 0, v[66:67]
	v_lshlrev_b32_e32 v4, 13, v4
	v_mov_b32_e32 v5, v67
	v_lshl_add_u64 v[62:63], v[2:3], 0, v[4:5]
	v_add_co_u32_e32 v6, vcc, s34, v62
	s_lshl_b32 s25, s58, 1
	s_nop 0
	v_addc_co_u32_e32 v7, vcc, 0, v63, vcc
	v_add_co_u32_e32 v10, vcc, s35, v62
	global_load_dwordx4 v[2:5], v[62:63], off
	s_nop 0
	global_load_dwordx4 v[6:9], v[6:7], off
	v_addc_co_u32_e32 v11, vcc, 0, v63, vcc
	v_add_co_u32_e32 v14, vcc, s36, v62
	s_add_u32 s56, s52, s25
	s_nop 0
	v_addc_co_u32_e32 v15, vcc, 0, v63, vcc
	v_add_co_u32_e32 v18, vcc, s37, v62
	global_load_dwordx4 v[10:13], v[10:11], off
	s_nop 0
	global_load_dwordx4 v[14:17], v[14:15], off
	v_addc_co_u32_e32 v19, vcc, 0, v63, vcc
	v_add_co_u32_e32 v22, vcc, s38, v62
	s_addc_u32 s57, s53, 0
	s_nop 0
	v_addc_co_u32_e32 v23, vcc, 0, v63, vcc
	v_add_co_u32_e32 v26, vcc, s39, v62
	global_load_dwordx4 v[18:21], v[18:19], off
	s_nop 0
	global_load_dwordx4 v[22:25], v[22:23], off
	v_addc_co_u32_e32 v27, vcc, 0, v63, vcc
	v_add_co_u32_e32 v30, vcc, s40, v62
	v_mov_b32_e32 v69, v67
	s_nop 0
	v_addc_co_u32_e32 v31, vcc, 0, v63, vcc
	v_add_co_u32_e32 v34, vcc, s41, v62
	global_load_dwordx4 v[26:29], v[26:27], off
	s_nop 0
	global_load_dwordx4 v[30:33], v[30:31], off
	v_addc_co_u32_e32 v35, vcc, 0, v63, vcc
	v_add_co_u32_e32 v38, vcc, s42, v62
	s_nop 1
	v_addc_co_u32_e32 v39, vcc, 0, v63, vcc
	v_add_co_u32_e32 v42, vcc, s43, v62
	global_load_dwordx4 v[34:37], v[34:35], off
	s_nop 0
	global_load_dwordx4 v[38:41], v[38:39], off
	v_addc_co_u32_e32 v43, vcc, 0, v63, vcc
	v_add_co_u32_e32 v46, vcc, s44, v62
	s_nop 1
	v_addc_co_u32_e32 v47, vcc, 0, v63, vcc
	v_add_co_u32_e32 v50, vcc, s45, v62
	global_load_dwordx4 v[42:45], v[42:43], off
	s_nop 0
	global_load_dwordx4 v[46:49], v[46:47], off
	v_addc_co_u32_e32 v51, vcc, 0, v63, vcc
	v_add_co_u32_e32 v54, vcc, s46, v62
	s_nop 1
	v_addc_co_u32_e32 v55, vcc, 0, v63, vcc
	global_load_dwordx4 v[50:53], v[50:51], off
	s_nop 0
	global_load_dwordx4 v[54:57], v[54:55], off
	v_add_co_u32_e32 v58, vcc, s47, v62
	s_nop 1
	v_addc_co_u32_e32 v59, vcc, 0, v63, vcc
	global_load_dwordx4 v[58:61], v[58:59], off
	v_add_co_u32_e32 v62, vcc, s48, v62
	s_nop 1
	v_addc_co_u32_e32 v63, vcc, 0, v63, vcc
	global_load_dwordx4 v[62:65], v[62:63], off
	s_waitcnt vmcnt(15)
	ds_write2_b32 v73, v2, v3 offset1:1
	ds_write2_b32 v73, v4, v5 offset0:2 offset1:3
	s_waitcnt vmcnt(14)
	ds_write2_b32 v83, v6, v7 offset1:1
	ds_write2_b32 v84, v8, v9 offset1:1
	s_waitcnt vmcnt(13)
	ds_write2_b32 v85, v10, v11 offset1:1
	ds_write2_b32 v86, v12, v13 offset1:1
	s_waitcnt vmcnt(12)
	ds_write2_b32 v87, v14, v15 offset1:1
	ds_write2_b32 v88, v16, v17 offset1:1
	s_waitcnt vmcnt(11)
	ds_write2_b32 v89, v18, v19 offset1:1
	ds_write2_b32 v90, v20, v21 offset1:1
	s_waitcnt vmcnt(10)
	ds_write2_b32 v91, v22, v23 offset1:1
	ds_write2_b32 v92, v24, v25 offset1:1
	s_waitcnt vmcnt(9)
	ds_write2_b32 v93, v26, v27 offset1:1
	ds_write2_b32 v94, v28, v29 offset1:1
	s_waitcnt vmcnt(8)
	ds_write2_b32 v95, v30, v31 offset1:1
	ds_write2_b32 v96, v32, v33 offset1:1
	s_waitcnt vmcnt(7)
	ds_write2_b32 v97, v34, v35 offset1:1
	ds_write2_b32 v98, v36, v37 offset1:1
	s_waitcnt vmcnt(6)
	ds_write2_b32 v99, v38, v39 offset1:1
	ds_write2_b32 v100, v40, v41 offset1:1
	s_waitcnt vmcnt(5)
	ds_write2_b32 v101, v42, v43 offset1:1
	ds_write2_b32 v102, v44, v45 offset1:1
	s_waitcnt vmcnt(4)
	ds_write2_b32 v103, v46, v47 offset1:1
	ds_write2_b32 v104, v48, v49 offset1:1
	s_waitcnt vmcnt(3)
	ds_write2_b32 v105, v50, v51 offset1:1
	ds_write2_b32 v106, v52, v53 offset1:1
	s_waitcnt vmcnt(2)
	ds_write2_b32 v107, v54, v55 offset1:1
	ds_write2_b32 v108, v56, v57 offset1:1
	s_waitcnt vmcnt(1)
	ds_write2_b32 v109, v58, v59 offset1:1
	ds_write2_b32 v110, v60, v61 offset1:1
	s_waitcnt vmcnt(0)
	ds_write2_b32 v111, v62, v63 offset1:1
	ds_write2_b32 v112, v64, v65 offset1:1
	s_waitcnt lgkmcnt(0)
; #define LAS __attribute__((address_space(3)))
; __device__ __forceinline__ unsigned pk2(float lo, float hi) { return pg8::cvt_pk_bf16(lo, hi); }
; __device__ __forceinline__ void p0_transpose_item(const float* __restrict__ W, const float* __restrict__ gain, int K, int N, bf16* __restrict__ WT, int mode, LAS float* scr, int item, int lane) {
;     ...
;     for (int j = 0; j < 8; ++j) { const int n = (lane >> 3) + 8 * j; const LAS float* s = scr + (8 * c) * 65 + n;
;         v4u o; o.x = pk2(s[0 * 65], s[1 * 65]); o.y = pk2(s[2 * 65], s[3 * 65]); o.z = pk2(s[4 * 65], s[5 * 65]); o.w = pk2(s[6 * 65], s[7 * 65]);
;         *(v4u*)(WT + (size_t)(rowbase + n) * K + k0 + 8 * c) = o; }
;     asm volatile("s_waitcnt lgkmcnt(0)" ::: "memory");
	ds_read2_b32 v[150:151], v75 offset1:65
	ds_read2_b32 v[152:153], v75 offset0:130 offset1:195
	ds_read2_b32 v[154:155], v113 offset0:4 offset1:69
	ds_read2_b32 v[156:157], v113 offset0:134 offset1:199
	ds_read2_b32 v[158:159], v75 offset0:8 offset1:73
	ds_read2_b32 v[160:161], v75 offset0:138 offset1:203
	ds_read2_b32 v[162:163], v113 offset0:12 offset1:77
	ds_read2_b32 v[164:165], v113 offset0:142 offset1:207
	ds_read2_b32 v[166:167], v75 offset0:16 offset1:81
	ds_read2_b32 v[168:169], v75 offset0:146 offset1:211
	ds_read2_b32 v[170:171], v113 offset0:20 offset1:85
	ds_read2_b32 v[172:173], v113 offset0:150 offset1:215
	ds_read2_b32 v[174:175], v75 offset0:24 offset1:89
	ds_read2_b32 v[176:177], v75 offset0:154 offset1:219
	ds_read2_b32 v[178:179], v113 offset0:28 offset1:93
	ds_read2_b32 v[180:181], v113 offset0:158 offset1:223
	ds_read2_b32 v[182:183], v75 offset0:32 offset1:97
	ds_read2_b32 v[184:185], v75 offset0:162 offset1:227
	ds_read2_b32 v[186:187], v113 offset0:36 offset1:101
	ds_read2_b32 v[188:189], v113 offset0:166 offset1:231
	ds_read2_b32 v[190:191], v75 offset0:40 offset1:105
	ds_read2_b32 v[192:193], v75 offset0:170 offset1:235
	ds_read2_b32 v[194:195], v113 offset0:44 offset1:109
	ds_read2_b32 v[196:197], v113 offset0:174 offset1:239
	ds_read2_b32 v[198:199], v75 offset0:48 offset1:113
	ds_read2_b32 v[200:201], v75 offset0:178 offset1:243
	ds_read2_b32 v[202:203], v113 offset0:52 offset1:117
	ds_read2_b32 v[204:205], v113 offset0:182 offset1:247
	ds_read2_b32 v[206:207], v75 offset0:56 offset1:121
	ds_read2_b32 v[208:209], v75 offset0:186 offset1:251
	ds_read2_b32 v[210:211], v113 offset0:60 offset1:125
	ds_read2_b32 v[212:213], v113 offset0:190 offset1:255
	s_waitcnt lgkmcnt(15)
	v_cvt_pk_bf16_f32 v214, v150, v151
	s_waitcnt lgkmcnt(15)
	v_cvt_pk_bf16_f32 v215, v152, v153
	s_waitcnt lgkmcnt(15)
	v_cvt_pk_bf16_f32 v216, v154, v155
	s_waitcnt lgkmcnt(15)
	v_cvt_pk_bf16_f32 v217, v156, v157
	v_or_b32_e32 v6, s24, v74
	v_lshl_add_u64 v[8:9], s[56:57], 0, v[68:69]
	v_mul_u32_u24_e32 v10, 0x1600, v6
	v_lshl_add_u64 v[8:9], v[8:9], 0, s[10:11]
	v_lshlrev_b32_e32 v10, 1, v10
	v_mov_b32_e32 v11, v67
	v_lshl_add_u64 v[10:11], v[8:9], 0, v[10:11]
	global_store_dwordx4 v[10:11], v[214:217], off
	v_mov_b32_e32 v11, v67
	s_waitcnt lgkmcnt(15)
	v_cvt_pk_bf16_f32 v218, v158, v159
	s_waitcnt lgkmcnt(15)
	v_cvt_pk_bf16_f32 v219, v160, v161
	s_waitcnt lgkmcnt(15)
	v_cvt_pk_bf16_f32 v220, v162, v163
	s_waitcnt lgkmcnt(15)
	v_cvt_pk_bf16_f32 v221, v164, v165
	v_or_b32_e32 v6, s24, v76
	v_mul_u32_u24_e32 v10, 0x1600, v6
	v_lshlrev_b32_e32 v10, 1, v10
	v_lshl_add_u64 v[10:11], v[8:9], 0, v[10:11]
	global_store_dwordx4 v[10:11], v[218:221], off
	v_mov_b32_e32 v11, v67
	s_waitcnt lgkmcnt(15)
	v_cvt_pk_bf16_f32 v222, v166, v167
	s_waitcnt lgkmcnt(15)
	v_cvt_pk_bf16_f32 v223, v168, v169
	s_waitcnt lgkmcnt(15)
	v_cvt_pk_bf16_f32 v224, v170, v171
	s_waitcnt lgkmcnt(15)
	v_cvt_pk_bf16_f32 v225, v172, v173
	v_or_b32_e32 v6, s24, v77
	v_mul_u32_u24_e32 v10, 0x1600, v6
	v_lshlrev_b32_e32 v10, 1, v10
	v_lshl_add_u64 v[10:11], v[8:9], 0, v[10:11]
	global_store_dwordx4 v[10:11], v[222:225], off
	v_mov_b32_e32 v11, v67
	s_waitcnt lgkmcnt(15)
	v_cvt_pk_bf16_f32 v226, v174, v175
	s_waitcnt lgkmcnt(15)
	v_cvt_pk_bf16_f32 v227, v176, v177
	s_waitcnt lgkmcnt(15)
	v_cvt_pk_bf16_f32 v228, v178, v179
	s_waitcnt lgkmcnt(15)
	v_cvt_pk_bf16_f32 v229, v180, v181
	v_or_b32_e32 v6, s24, v78
	v_mul_u32_u24_e32 v10, 0x1600, v6
	v_lshlrev_b32_e32 v10, 1, v10
	v_lshl_add_u64 v[10:11], v[8:9], 0, v[10:11]
	global_store_dwordx4 v[10:11], v[226:229], off
	v_mov_b32_e32 v11, v67
	s_waitcnt lgkmcnt(15)
	v_cvt_pk_bf16_f32 v230, v182, v183
	s_waitcnt lgkmcnt(14)
	v_cvt_pk_bf16_f32 v231, v184, v185
	s_waitcnt lgkmcnt(13)
	v_cvt_pk_bf16_f32 v232, v186, v187
	s_waitcnt lgkmcnt(12)
	v_cvt_pk_bf16_f32 v233, v188, v189
	v_or_b32_e32 v6, s24, v79
	v_mul_u32_u24_e32 v10, 0x1600, v6
	v_lshlrev_b32_e32 v10, 1, v10
	v_lshl_add_u64 v[10:11], v[8:9], 0, v[10:11]
	global_store_dwordx4 v[10:11], v[230:233], off
	v_or_b32_e32 v10, s24, v80
	v_mul_u32_u24_e32 v10, 0x1600, v10
	s_waitcnt lgkmcnt(11)
	v_cvt_pk_bf16_f32 v234, v190, v191
	v_mov_b32_e32 v11, v67
	v_lshlrev_b32_e32 v10, 1, v10
	s_waitcnt lgkmcnt(10)
	v_cvt_pk_bf16_f32 v235, v192, v193
	v_lshl_add_u64 v[10:11], v[8:9], 0, v[10:11]
	s_waitcnt lgkmcnt(9)
	v_cvt_pk_bf16_f32 v236, v194, v195
	s_waitcnt lgkmcnt(8)
	v_cvt_pk_bf16_f32 v237, v196, v197
	global_store_dwordx4 v[10:11], v[234:237], off
	v_or_b32_e32 v10, s24, v81
	s_waitcnt lgkmcnt(7)
	v_cvt_pk_bf16_f32 v238, v198, v199
	v_mul_u32_u24_e32 v10, 0x1600, v10
	s_waitcnt lgkmcnt(6)
	v_cvt_pk_bf16_f32 v239, v200, v201
	v_mov_b32_e32 v11, v67
	v_lshlrev_b32_e32 v10, 1, v10
	s_waitcnt lgkmcnt(5)
	v_cvt_pk_bf16_f32 v240, v202, v203
	s_waitcnt lgkmcnt(4)
	v_cvt_pk_bf16_f32 v241, v204, v205
	v_lshl_add_u64 v[10:11], v[8:9], 0, v[10:11]
	global_store_dwordx4 v[10:11], v[238:241], off
	v_mov_b32_e32 v11, v67
	s_waitcnt lgkmcnt(3)
	v_cvt_pk_bf16_f32 v242, v206, v207
	s_waitcnt lgkmcnt(2)
	v_cvt_pk_bf16_f32 v243, v208, v209
	s_waitcnt lgkmcnt(1)
	v_cvt_pk_bf16_f32 v244, v210, v211
	v_or_b32_e32 v5, s24, v82
	v_mul_u32_u24_e32 v5, 0x1600, v5
	v_lshlrev_b32_e32 v10, 1, v5
	s_waitcnt lgkmcnt(0)
	v_cvt_pk_bf16_f32 v245, v212, v213
	v_lshl_add_u64 v[6:7], v[8:9], 0, v[10:11]
	global_store_dwordx4 v[6:7], v[242:245], off
	s_waitcnt lgkmcnt(0)
	s_mov_b64 s[24:25], 0

; #define LAS __attribute__((address_space(3)))
; __device__ __forceinline__ unsigned pk2(float lo, float hi) { return pg8::cvt_pk_bf16(lo, hi); }
; __device__ __forceinline__ void p0_transpose_item(const float* __restrict__ W, const float* __restrict__ gain, int K, int N, bf16* __restrict__ WT, int mode, LAS float* scr, int item, int lane) {
;     ...
;     for (int i = 0; i < 16; ++i) { LAS float* d = scr + (4 * i + lr) * 65 + lc4; d[0] = v[i].x; d[1] = v[i].y; d[2] = v[i].z; d[3] = v[i].w; }
;     asm volatile("s_waitcnt lgkmcnt(0)" ::: "memory");
;     const int c = lane & 7;
;     const int rowbase = mode == 0 ? n0 : (((n0 >> 7) << 8) + (n0 & 127) + (mode == 2 ? 128 : 0));
; #pragma unroll
;     for (int j = 0; j < 8; ++j) { const int n = (lane >> 3) + 8 * j; const LAS float* s = scr + (8 * c) * 65 + n;
;         v4u o; o.x = pk2(s[0 * 65], s[1 * 65]); o.y = pk2(s[2 * 65], s[3 * 65]); o.z = pk2(s[4 * 65], s[5 * 65]); o.w = pk2(s[6 * 65], s[7 * 65]);
;         *(v4u*)(WT + (size_t)(rowbase + n) * K + k0 + 8 * c) = o; }
;     asm volatile("s_waitcnt lgkmcnt(0)" ::: "memory");
.LBB0_15:
	s_lshl_b32 s24, s56, 6
	s_lshl_b32 s25, s56, 7
	s_and_b32 s24, s24, 64
	s_or_b32 s24, s24, s25
	s_and_b32 s25, 0xffff, s55
	s_waitcnt vmcnt(15)
	ds_write2_b32 v73, v6, v7 offset1:1
	ds_write2_b32 v73, v8, v9 offset0:2 offset1:3
	s_waitcnt vmcnt(14)
	ds_write2_b32 v83, v2, v3 offset1:1
	ds_write2_b32 v84, v4, v5 offset1:1
	s_waitcnt vmcnt(13)
	ds_write2_b32 v85, v14, v15 offset1:1
	ds_write2_b32 v86, v16, v17 offset1:1
	s_waitcnt vmcnt(12)
	ds_write2_b32 v87, v10, v11 offset1:1
	ds_write2_b32 v88, v12, v13 offset1:1
	s_waitcnt vmcnt(11)
	ds_write2_b32 v89, v22, v23 offset1:1
	ds_write2_b32 v90, v24, v25 offset1:1
	s_waitcnt vmcnt(10)
	ds_write2_b32 v91, v18, v19 offset1:1
	ds_write2_b32 v92, v20, v21 offset1:1
	s_waitcnt vmcnt(9)
	ds_write2_b32 v93, v30, v31 offset1:1
	ds_write2_b32 v94, v32, v33 offset1:1
	s_waitcnt vmcnt(8)
	ds_write2_b32 v95, v26, v27 offset1:1
	ds_write2_b32 v96, v28, v29 offset1:1
	s_waitcnt vmcnt(7)
	ds_write2_b32 v97, v38, v39 offset1:1
	ds_write2_b32 v98, v40, v41 offset1:1
	s_waitcnt vmcnt(6)
	ds_write2_b32 v99, v34, v35 offset1:1
	ds_write2_b32 v100, v36, v37 offset1:1
	s_waitcnt vmcnt(5)
	ds_write2_b32 v101, v46, v47 offset1:1
	ds_write2_b32 v102, v48, v49 offset1:1
	s_waitcnt vmcnt(4)
	ds_write2_b32 v103, v42, v43 offset1:1
	ds_write2_b32 v104, v44, v45 offset1:1
	s_waitcnt vmcnt(3)
	ds_write2_b32 v105, v54, v55 offset1:1
	ds_write2_b32 v106, v56, v57 offset1:1
	s_waitcnt vmcnt(2)
	ds_write2_b32 v107, v50, v51 offset1:1
	ds_write2_b32 v108, v52, v53 offset1:1
	s_waitcnt vmcnt(1)
	ds_write2_b32 v109, v62, v63 offset1:1
	ds_write2_b32 v110, v64, v65 offset1:1
	s_waitcnt vmcnt(0)
	ds_write2_b32 v111, v58, v59 offset1:1
	ds_write2_b32 v112, v60, v61 offset1:1
	s_bitset1_b32 s24, 7
	s_lshl_b32 s25, s25, 1
	s_waitcnt lgkmcnt(0)
	s_add_u32 s56, s52, s25
	ds_read2_b32 v[150:151], v75 offset1:65
	ds_read2_b32 v[152:153], v75 offset0:130 offset1:195
	ds_read2_b32 v[154:155], v113 offset0:4 offset1:69
	ds_read2_b32 v[156:157], v113 offset0:134 offset1:199
	ds_read2_b32 v[158:159], v75 offset0:8 offset1:73
	ds_read2_b32 v[160:161], v75 offset0:138 offset1:203
	ds_read2_b32 v[162:163], v113 offset0:12 offset1:77
	ds_read2_b32 v[164:165], v113 offset0:142 offset1:207
	ds_read2_b32 v[166:167], v75 offset0:16 offset1:81
	ds_read2_b32 v[168:169], v75 offset0:146 offset1:211
	ds_read2_b32 v[170:171], v113 offset0:20 offset1:85
	ds_read2_b32 v[172:173], v113 offset0:150 offset1:215
	ds_read2_b32 v[174:175], v75 offset0:24 offset1:89
	ds_read2_b32 v[176:177], v75 offset0:154 offset1:219
	ds_read2_b32 v[178:179], v113 offset0:28 offset1:93
	ds_read2_b32 v[180:181], v113 offset0:158 offset1:223
	ds_read2_b32 v[182:183], v75 offset0:32 offset1:97
	ds_read2_b32 v[184:185], v75 offset0:162 offset1:227
	ds_read2_b32 v[186:187], v113 offset0:36 offset1:101
	ds_read2_b32 v[188:189], v113 offset0:166 offset1:231
	ds_read2_b32 v[190:191], v75 offset0:40 offset1:105
	ds_read2_b32 v[192:193], v75 offset0:170 offset1:235
	ds_read2_b32 v[194:195], v113 offset0:44 offset1:109
	ds_read2_b32 v[196:197], v113 offset0:174 offset1:239
	ds_read2_b32 v[198:199], v75 offset0:48 offset1:113
	ds_read2_b32 v[200:201], v75 offset0:178 offset1:243
	ds_read2_b32 v[202:203], v113 offset0:52 offset1:117
	ds_read2_b32 v[204:205], v113 offset0:182 offset1:247
	ds_read2_b32 v[206:207], v75 offset0:56 offset1:121
	ds_read2_b32 v[208:209], v75 offset0:186 offset1:251
	ds_read2_b32 v[210:211], v113 offset0:60 offset1:125
	ds_read2_b32 v[212:213], v113 offset0:190 offset1:255
	s_addc_u32 s57, s53, 0
	v_mov_b32_e32 v69, v67
	s_waitcnt lgkmcnt(15)
	v_cvt_pk_bf16_f32 v214, v150, v151
	v_lshl_add_u64 v[8:9], s[56:57], 0, v[68:69]
	v_or_b32_e32 v10, s24, v74
	s_waitcnt lgkmcnt(15)
	v_cvt_pk_bf16_f32 v215, v152, v153
	v_lshl_add_u64 v[8:9], v[8:9], 0, s[12:13]
	v_lshlrev_b32_e32 v10, 12, v10
	v_mov_b32_e32 v11, v67
	s_waitcnt lgkmcnt(15)
	v_cvt_pk_bf16_f32 v216, v154, v155
	s_waitcnt lgkmcnt(15)
	v_cvt_pk_bf16_f32 v217, v156, v157
	v_lshl_add_u64 v[10:11], v[8:9], 0, v[10:11]
	global_store_dwordx4 v[10:11], v[214:217], off
	v_or_b32_e32 v10, s24, v76
	v_lshlrev_b32_e32 v10, 12, v10
	s_waitcnt lgkmcnt(15)
	v_cvt_pk_bf16_f32 v218, v158, v159
	s_waitcnt lgkmcnt(15)
	v_cvt_pk_bf16_f32 v219, v160, v161
	v_mov_b32_e32 v11, v67
	s_waitcnt lgkmcnt(15)
	v_cvt_pk_bf16_f32 v220, v162, v163
	s_waitcnt lgkmcnt(15)
	v_cvt_pk_bf16_f32 v221, v164, v165
	v_lshl_add_u64 v[10:11], v[8:9], 0, v[10:11]
	global_store_dwordx4 v[10:11], v[218:221], off
	v_or_b32_e32 v10, s24, v77
	v_lshlrev_b32_e32 v10, 12, v10
	s_waitcnt lgkmcnt(15)
	v_cvt_pk_bf16_f32 v222, v166, v167
	s_waitcnt lgkmcnt(15)
	v_cvt_pk_bf16_f32 v223, v168, v169
	v_mov_b32_e32 v11, v67
	s_waitcnt lgkmcnt(15)
	v_cvt_pk_bf16_f32 v224, v170, v171
	s_waitcnt lgkmcnt(15)
	v_cvt_pk_bf16_f32 v225, v172, v173
	v_lshl_add_u64 v[10:11], v[8:9], 0, v[10:11]
	global_store_dwordx4 v[10:11], v[222:225], off
	v_or_b32_e32 v10, s24, v78
	v_lshlrev_b32_e32 v10, 12, v10
	s_waitcnt lgkmcnt(15)
	v_cvt_pk_bf16_f32 v226, v174, v175
	s_waitcnt lgkmcnt(15)
	v_cvt_pk_bf16_f32 v227, v176, v177
	v_mov_b32_e32 v11, v67
	s_waitcnt lgkmcnt(15)
	v_cvt_pk_bf16_f32 v228, v178, v179
	s_waitcnt lgkmcnt(15)
	v_cvt_pk_bf16_f32 v229, v180, v181
	v_lshl_add_u64 v[10:11], v[8:9], 0, v[10:11]
	global_store_dwordx4 v[10:11], v[226:229], off
	v_or_b32_e32 v10, s24, v79
	v_lshlrev_b32_e32 v10, 12, v10
	s_waitcnt lgkmcnt(15)
	v_cvt_pk_bf16_f32 v230, v182, v183
	s_waitcnt lgkmcnt(14)
	v_cvt_pk_bf16_f32 v231, v184, v185
	v_mov_b32_e32 v11, v67
	s_waitcnt lgkmcnt(13)
	v_cvt_pk_bf16_f32 v232, v186, v187
	s_waitcnt lgkmcnt(12)
	v_cvt_pk_bf16_f32 v233, v188, v189
	v_lshl_add_u64 v[10:11], v[8:9], 0, v[10:11]
	global_store_dwordx4 v[10:11], v[230:233], off
	v_or_b32_e32 v10, s24, v80
	v_mov_b32_e32 v11, v67
	s_waitcnt lgkmcnt(11)
	v_cvt_pk_bf16_f32 v234, v190, v191
	s_waitcnt lgkmcnt(10)
	v_cvt_pk_bf16_f32 v235, v192, v193
	v_lshlrev_b32_e32 v10, 12, v10
	s_waitcnt lgkmcnt(9)
	v_cvt_pk_bf16_f32 v236, v194, v195
	s_waitcnt lgkmcnt(8)
	v_cvt_pk_bf16_f32 v237, v196, v197
	v_lshl_add_u64 v[10:11], v[8:9], 0, v[10:11]
	global_store_dwordx4 v[10:11], v[234:237], off
	v_or_b32_e32 v10, s24, v81
	v_mov_b32_e32 v11, v67
	s_waitcnt lgkmcnt(7)
	v_cvt_pk_bf16_f32 v238, v198, v199
	s_waitcnt lgkmcnt(6)
	v_cvt_pk_bf16_f32 v239, v200, v201
	v_lshlrev_b32_e32 v10, 12, v10
	s_waitcnt lgkmcnt(5)
	v_cvt_pk_bf16_f32 v240, v202, v203
	s_waitcnt lgkmcnt(4)
	v_cvt_pk_bf16_f32 v241, v204, v205
	v_lshl_add_u64 v[10:11], v[8:9], 0, v[10:11]
	global_store_dwordx4 v[10:11], v[238:241], off
	v_mov_b32_e32 v11, v67
	s_waitcnt lgkmcnt(3)
	v_cvt_pk_bf16_f32 v242, v206, v207
	s_waitcnt lgkmcnt(2)
	v_cvt_pk_bf16_f32 v243, v208, v209
	s_waitcnt lgkmcnt(1)
	v_cvt_pk_bf16_f32 v244, v210, v211
	v_or_b32_e32 v5, s24, v82
	v_lshlrev_b32_e32 v10, 12, v5
	s_waitcnt lgkmcnt(0)
	v_cvt_pk_bf16_f32 v245, v212, v213
	v_lshl_add_u64 v[6:7], v[8:9], 0, v[10:11]
	global_store_dwordx4 v[6:7], v[242:245], off
	s_waitcnt lgkmcnt(0)

; #define LAS __attribute__((address_space(3)))
; __device__ __forceinline__ unsigned pk2(float lo, float hi) { return pg8::cvt_pk_bf16(lo, hi); }
; __device__ __forceinline__ void p0_transpose_item(const float* __restrict__ W, const float* __restrict__ gain, int K, int N, bf16* __restrict__ WT, int mode, LAS float* scr, int item, int lane) {
;     ...
;     for (int i = 0; i < 16; ++i) { LAS float* d = scr + (4 * i + lr) * 65 + lc4; d[0] = v[i].x; d[1] = v[i].y; d[2] = v[i].z; d[3] = v[i].w; }
;     asm volatile("s_waitcnt lgkmcnt(0)" ::: "memory");
;     const int c = lane & 7;
;     const int rowbase = mode == 0 ? n0 : (((n0 >> 7) << 8) + (n0 & 127) + (mode == 2 ? 128 : 0));
; #pragma unroll
;     for (int j = 0; j < 8; ++j) { const int n = (lane >> 3) + 8 * j; const LAS float* s = scr + (8 * c) * 65 + n;
;         v4u o; o.x = pk2(s[0 * 65], s[1 * 65]); o.y = pk2(s[2 * 65], s[3 * 65]); o.z = pk2(s[4 * 65], s[5 * 65]); o.w = pk2(s[6 * 65], s[7 * 65]);
;         *(v4u*)(WT + (size_t)(rowbase + n) * K + k0 + 8 * c) = o; }
;     asm volatile("s_waitcnt lgkmcnt(0)" ::: "memory");
.LBB0_20:
	s_lshl_b32 s24, s56, 6
	s_lshl_b32 s25, s56, 7
	s_and_b32 s25, s25, 0x3f00
	s_and_b32 s24, s24, 64
	s_or_b32 s24, s24, s25
	s_and_b32 s25, 0xffff, s55
	s_waitcnt vmcnt(15)
	ds_write2_b32 v73, v6, v7 offset1:1
	ds_write2_b32 v73, v8, v9 offset0:2 offset1:3
	s_waitcnt vmcnt(14)
	ds_write2_b32 v83, v2, v3 offset1:1
	ds_write2_b32 v84, v4, v5 offset1:1
	s_waitcnt vmcnt(13)
	ds_write2_b32 v85, v14, v15 offset1:1
	ds_write2_b32 v86, v16, v17 offset1:1
	s_waitcnt vmcnt(12)
	ds_write2_b32 v87, v10, v11 offset1:1
	ds_write2_b32 v88, v12, v13 offset1:1
	s_waitcnt vmcnt(11)
	ds_write2_b32 v89, v22, v23 offset1:1
	ds_write2_b32 v90, v24, v25 offset1:1
	s_waitcnt vmcnt(10)
	ds_write2_b32 v91, v18, v19 offset1:1
	ds_write2_b32 v92, v20, v21 offset1:1
	s_waitcnt vmcnt(9)
	ds_write2_b32 v93, v30, v31 offset1:1
	ds_write2_b32 v94, v32, v33 offset1:1
	s_waitcnt vmcnt(8)
	ds_write2_b32 v95, v26, v27 offset1:1
	ds_write2_b32 v96, v28, v29 offset1:1
	s_waitcnt vmcnt(7)
	ds_write2_b32 v97, v38, v39 offset1:1
	ds_write2_b32 v98, v40, v41 offset1:1
	s_waitcnt vmcnt(6)
	ds_write2_b32 v99, v34, v35 offset1:1
	ds_write2_b32 v100, v36, v37 offset1:1
	s_waitcnt vmcnt(5)
	ds_write2_b32 v101, v46, v47 offset1:1
	ds_write2_b32 v102, v48, v49 offset1:1
	s_waitcnt vmcnt(4)
	ds_write2_b32 v103, v42, v43 offset1:1
	ds_write2_b32 v104, v44, v45 offset1:1
	s_waitcnt vmcnt(3)
	ds_write2_b32 v105, v54, v55 offset1:1
	ds_write2_b32 v106, v56, v57 offset1:1
	s_waitcnt vmcnt(2)
	ds_write2_b32 v107, v50, v51 offset1:1
	ds_write2_b32 v108, v52, v53 offset1:1
	s_waitcnt vmcnt(1)
	ds_write2_b32 v109, v62, v63 offset1:1
	ds_write2_b32 v110, v64, v65 offset1:1
	s_waitcnt vmcnt(0)
	ds_write2_b32 v111, v58, v59 offset1:1
	ds_write2_b32 v112, v60, v61 offset1:1
	s_lshl_b32 s25, s25, 1
	s_waitcnt lgkmcnt(0)
	s_add_u32 s56, s52, s25
	ds_read2_b32 v[150:151], v75 offset1:65
	ds_read2_b32 v[152:153], v75 offset0:130 offset1:195
	ds_read2_b32 v[154:155], v113 offset0:4 offset1:69
	ds_read2_b32 v[156:157], v113 offset0:134 offset1:199
	ds_read2_b32 v[158:159], v75 offset0:8 offset1:73
	ds_read2_b32 v[160:161], v75 offset0:138 offset1:203
	ds_read2_b32 v[162:163], v113 offset0:12 offset1:77
	ds_read2_b32 v[164:165], v113 offset0:142 offset1:207
	ds_read2_b32 v[166:167], v75 offset0:16 offset1:81
	ds_read2_b32 v[168:169], v75 offset0:146 offset1:211
	ds_read2_b32 v[170:171], v113 offset0:20 offset1:85
	ds_read2_b32 v[172:173], v113 offset0:150 offset1:215
	ds_read2_b32 v[174:175], v75 offset0:24 offset1:89
	ds_read2_b32 v[176:177], v75 offset0:154 offset1:219
	ds_read2_b32 v[178:179], v113 offset0:28 offset1:93
	ds_read2_b32 v[180:181], v113 offset0:158 offset1:223
	ds_read2_b32 v[182:183], v75 offset0:32 offset1:97
	ds_read2_b32 v[184:185], v75 offset0:162 offset1:227
	ds_read2_b32 v[186:187], v113 offset0:36 offset1:101
	ds_read2_b32 v[188:189], v113 offset0:166 offset1:231
	ds_read2_b32 v[190:191], v75 offset0:40 offset1:105
	ds_read2_b32 v[192:193], v75 offset0:170 offset1:235
	ds_read2_b32 v[194:195], v113 offset0:44 offset1:109
	ds_read2_b32 v[196:197], v113 offset0:174 offset1:239
	ds_read2_b32 v[198:199], v75 offset0:48 offset1:113
	ds_read2_b32 v[200:201], v75 offset0:178 offset1:243
	ds_read2_b32 v[202:203], v113 offset0:52 offset1:117
	ds_read2_b32 v[204:205], v113 offset0:182 offset1:247
	ds_read2_b32 v[206:207], v75 offset0:56 offset1:121
	ds_read2_b32 v[208:209], v75 offset0:186 offset1:251
	ds_read2_b32 v[210:211], v113 offset0:60 offset1:125
	ds_read2_b32 v[212:213], v113 offset0:190 offset1:255
	s_addc_u32 s57, s53, 0
	v_mov_b32_e32 v69, v67
	s_waitcnt lgkmcnt(15)
	v_cvt_pk_bf16_f32 v214, v150, v151
	v_lshl_add_u64 v[8:9], s[56:57], 0, v[68:69]
	v_or_b32_e32 v10, s24, v74
	s_waitcnt lgkmcnt(15)
	v_cvt_pk_bf16_f32 v215, v152, v153
	v_lshl_add_u64 v[8:9], v[8:9], 0, s[12:13]
	v_lshlrev_b32_e32 v10, 12, v10
	v_mov_b32_e32 v11, v67
	s_waitcnt lgkmcnt(15)
	v_cvt_pk_bf16_f32 v216, v154, v155
	s_waitcnt lgkmcnt(15)
	v_cvt_pk_bf16_f32 v217, v156, v157
	v_lshl_add_u64 v[10:11], v[8:9], 0, v[10:11]
	global_store_dwordx4 v[10:11], v[214:217], off
	v_or_b32_e32 v10, s24, v76
	v_lshlrev_b32_e32 v10, 12, v10
	s_waitcnt lgkmcnt(15)
	v_cvt_pk_bf16_f32 v218, v158, v159
	s_waitcnt lgkmcnt(15)
	v_cvt_pk_bf16_f32 v219, v160, v161
	v_mov_b32_e32 v11, v67
	s_waitcnt lgkmcnt(15)
	v_cvt_pk_bf16_f32 v220, v162, v163
	s_waitcnt lgkmcnt(15)
	v_cvt_pk_bf16_f32 v221, v164, v165
	v_lshl_add_u64 v[10:11], v[8:9], 0, v[10:11]
	global_store_dwordx4 v[10:11], v[218:221], off
	v_or_b32_e32 v10, s24, v77
	v_lshlrev_b32_e32 v10, 12, v10
	s_waitcnt lgkmcnt(15)
	v_cvt_pk_bf16_f32 v222, v166, v167
	s_waitcnt lgkmcnt(15)
	v_cvt_pk_bf16_f32 v223, v168, v169
	v_mov_b32_e32 v11, v67
	s_waitcnt lgkmcnt(15)
	v_cvt_pk_bf16_f32 v224, v170, v171
	s_waitcnt lgkmcnt(15)
	v_cvt_pk_bf16_f32 v225, v172, v173
	v_lshl_add_u64 v[10:11], v[8:9], 0, v[10:11]
	global_store_dwordx4 v[10:11], v[222:225], off
	v_or_b32_e32 v10, s24, v78
	v_lshlrev_b32_e32 v10, 12, v10
	s_waitcnt lgkmcnt(15)
	v_cvt_pk_bf16_f32 v226, v174, v175
	s_waitcnt lgkmcnt(15)
	v_cvt_pk_bf16_f32 v227, v176, v177
	v_mov_b32_e32 v11, v67
	s_waitcnt lgkmcnt(15)
	v_cvt_pk_bf16_f32 v228, v178, v179
	s_waitcnt lgkmcnt(15)
	v_cvt_pk_bf16_f32 v229, v180, v181
	v_lshl_add_u64 v[10:11], v[8:9], 0, v[10:11]
	global_store_dwordx4 v[10:11], v[226:229], off
	v_or_b32_e32 v10, s24, v79
	v_lshlrev_b32_e32 v10, 12, v10
	s_waitcnt lgkmcnt(15)
	v_cvt_pk_bf16_f32 v230, v182, v183
	s_waitcnt lgkmcnt(14)
	v_cvt_pk_bf16_f32 v231, v184, v185
	v_mov_b32_e32 v11, v67
	s_waitcnt lgkmcnt(13)
	v_cvt_pk_bf16_f32 v232, v186, v187
	s_waitcnt lgkmcnt(12)
	v_cvt_pk_bf16_f32 v233, v188, v189
	v_lshl_add_u64 v[10:11], v[8:9], 0, v[10:11]
	global_store_dwordx4 v[10:11], v[230:233], off
	v_or_b32_e32 v10, s24, v80
	v_mov_b32_e32 v11, v67
	s_waitcnt lgkmcnt(11)
	v_cvt_pk_bf16_f32 v234, v190, v191
	s_waitcnt lgkmcnt(10)
	v_cvt_pk_bf16_f32 v235, v192, v193
	v_lshlrev_b32_e32 v10, 12, v10
	s_waitcnt lgkmcnt(9)
	v_cvt_pk_bf16_f32 v236, v194, v195
	s_waitcnt lgkmcnt(8)
	v_cvt_pk_bf16_f32 v237, v196, v197
	v_lshl_add_u64 v[10:11], v[8:9], 0, v[10:11]
	global_store_dwordx4 v[10:11], v[234:237], off
	v_or_b32_e32 v10, s24, v81
	v_mov_b32_e32 v11, v67
	s_waitcnt lgkmcnt(7)
	v_cvt_pk_bf16_f32 v238, v198, v199
	s_waitcnt lgkmcnt(6)
	v_cvt_pk_bf16_f32 v239, v200, v201
	v_lshlrev_b32_e32 v10, 12, v10
	s_waitcnt lgkmcnt(5)
	v_cvt_pk_bf16_f32 v240, v202, v203
	s_waitcnt lgkmcnt(4)
	v_cvt_pk_bf16_f32 v241, v204, v205
	v_lshl_add_u64 v[10:11], v[8:9], 0, v[10:11]
	global_store_dwordx4 v[10:11], v[238:241], off
	v_mov_b32_e32 v11, v67
	s_waitcnt lgkmcnt(3)
	v_cvt_pk_bf16_f32 v242, v206, v207
	s_waitcnt lgkmcnt(2)
	v_cvt_pk_bf16_f32 v243, v208, v209
	s_waitcnt lgkmcnt(1)
	v_cvt_pk_bf16_f32 v244, v210, v211
	v_or_b32_e32 v5, s24, v82
	v_lshlrev_b32_e32 v10, 12, v5
	s_waitcnt lgkmcnt(0)
	v_cvt_pk_bf16_f32 v245, v212, v213
	v_lshl_add_u64 v[6:7], v[8:9], 0, v[10:11]
	global_store_dwordx4 v[6:7], v[242:245], off
	s_waitcnt lgkmcnt(0)

; #define LAS __attribute__((address_space(3)))
; __device__ __forceinline__ void p0_transpose_item(const float* __restrict__ W, const float* __restrict__ gain, int K, int N, bf16* __restrict__ WT, int mode, LAS float* scr, int item, int lane) {
;     const int nblk = N / 64, kb = item / nblk, nb = item % nblk, k0 = 64 * kb, n0 = 64 * nb, lr = lane >> 4, lc4 = (lane & 15) * 4;
;     f32x4 v[16];
; #pragma unroll
;     for (int i = 0; i < 16; ++i) v[i] = *(const f32x4*)(W + (size_t)(k0 + 4 * i + lr) * N + n0 + lc4);
;     if (gain) {
; #pragma unroll
;         for (int i = 0; i < 16; ++i) v[i] = v[i] * gain[k0 + 4 * i + lr]; }
; #pragma unroll
;     for (int i = 0; i < 16; ++i) { LAS float* d = scr + (4 * i + lr) * 65 + lc4; d[0] = v[i].x; d[1] = v[i].y; d[2] = v[i].z; d[3] = v[i].w; }
;     asm volatile("s_waitcnt lgkmcnt(0)" ::: "memory");
; __device__ __forceinline__ void p0_prologue(const Args& a, LAS unsigned char* lds, int gw, int NGW, int lane, int wave) {
;     ...
;         if (r < I_A) { p0_transpose_item(a.in[2] + og, a.in[1] + l * DM, DM, DFF, (bf16*)(wl + W_GU1), 1, scr, r, lane); continue; } r -= I_A;
;         if (r < I_A) { p0_transpose_item(a.in[3] + og, a.in[1] + l * DM, DM, DFF, (bf16*)(wl + W_GU1), 2, scr, r, lane); continue; } r -= I_A;
;         if (r < I_D) { p0_transpose_item(a.in[4] + og, nullptr, DFF, DM, (bf16*)(wl + W_D1), 0, scr, r, lane); continue; } r -= I_D;
;         if (r < I_IN) { p0_transpose_item(a.in[6] + (size_t)l * DM * DIN, a.in[5] + l * DM, DM, DIN, (bf16*)(wl + W_IN), 0, scr, r, lane); continue; } r -= I_IN;
;         if (r < I_OUT) { p0_transpose_item(a.in[10] + (size_t)l * DM * DM, nullptr, DM, DM, (bf16*)(wl + W_OUT), 0, scr, r, lane); continue; } r -= I_OUT;
;         if (r < I_A) { p0_transpose_item(a.in[12] + og, a.in[11] + l * DM, DM, DFF, (bf16*)(wl + W_GU2), 1, scr, r, lane); continue; } r -= I_A;
;         if (r < I_A) { p0_transpose_item(a.in[13] + og, a.in[11] + l * DM, DM, DFF, (bf16*)(wl + W_GU2), 2, scr, r, lane); continue; } r -= I_A;
;         p0_transpose_item(a.in[14] + og, nullptr, DFF, DM, (bf16*)(wl + W_D2), 0, scr, r, lane);
.LBB0_22:
	s_andn2_b64 vcc, exec, s[24:25]
	s_cbranch_vccnz .LBB0_24
	s_lshl_b64 s[24:25], s[20:21], 24
	s_add_u32 s24, s80, s24
	s_mul_i32 s21, s20, 0xffff6000
	s_addc_u32 s25, s81, s25
	s_add_i32 s21, s31, s21
	s_addk_i32 s21, 0xd600
	s_and_b32 s55, s21, 0x1ffc0
	s_and_b32 s21, s29, 0x7c0
	s_lshl_b32 s56, s21, 2
	s_add_u32 s24, s24, s56
	v_or_b32_e32 v4, s55, v72
	s_addc_u32 s25, s25, 0
	v_lshl_add_u64 v[2:3], s[24:25], 0, v[66:67]
	v_lshlrev_b32_e32 v4, 13, v4
	v_mov_b32_e32 v5, v67
	v_lshl_add_u64 v[62:63], v[2:3], 0, v[4:5]
	v_add_co_u32_e32 v6, vcc, s34, v62
	s_lshl_b32 s24, s55, 1
	s_nop 0
	v_addc_co_u32_e32 v7, vcc, 0, v63, vcc
	v_add_co_u32_e32 v10, vcc, s35, v62
	global_load_dwordx4 v[2:5], v[62:63], off
	s_nop 0
	global_load_dwordx4 v[6:9], v[6:7], off
	v_addc_co_u32_e32 v11, vcc, 0, v63, vcc
	v_add_co_u32_e32 v14, vcc, s36, v62
	s_add_u32 s24, s52, s24
	s_nop 0
	v_addc_co_u32_e32 v15, vcc, 0, v63, vcc
	v_add_co_u32_e32 v18, vcc, s37, v62
	global_load_dwordx4 v[10:13], v[10:11], off
	s_nop 0
	global_load_dwordx4 v[14:17], v[14:15], off
	v_addc_co_u32_e32 v19, vcc, 0, v63, vcc
	v_add_co_u32_e32 v22, vcc, s38, v62
	s_addc_u32 s25, s53, 0
	s_nop 0
	v_addc_co_u32_e32 v23, vcc, 0, v63, vcc
	v_add_co_u32_e32 v26, vcc, s39, v62
	global_load_dwordx4 v[18:21], v[18:19], off
	s_nop 0
	global_load_dwordx4 v[22:25], v[22:23], off
	v_addc_co_u32_e32 v27, vcc, 0, v63, vcc
	v_add_co_u32_e32 v30, vcc, s40, v62
	v_mov_b32_e32 v69, v67
	s_nop 0
	v_addc_co_u32_e32 v31, vcc, 0, v63, vcc
	v_add_co_u32_e32 v34, vcc, s41, v62
	global_load_dwordx4 v[26:29], v[26:27], off
	s_nop 0
	global_load_dwordx4 v[30:33], v[30:31], off
	v_addc_co_u32_e32 v35, vcc, 0, v63, vcc
	v_add_co_u32_e32 v38, vcc, s42, v62
	s_nop 1
	v_addc_co_u32_e32 v39, vcc, 0, v63, vcc
	v_add_co_u32_e32 v42, vcc, s43, v62
	global_load_dwordx4 v[34:37], v[34:35], off
	s_nop 0
	global_load_dwordx4 v[38:41], v[38:39], off
	v_addc_co_u32_e32 v43, vcc, 0, v63, vcc
	v_add_co_u32_e32 v46, vcc, s44, v62
	s_nop 1
	v_addc_co_u32_e32 v47, vcc, 0, v63, vcc
	v_add_co_u32_e32 v50, vcc, s45, v62
	global_load_dwordx4 v[42:45], v[42:43], off
	s_nop 0
	global_load_dwordx4 v[46:49], v[46:47], off
	v_addc_co_u32_e32 v51, vcc, 0, v63, vcc
	v_add_co_u32_e32 v54, vcc, s46, v62
	s_nop 1
	v_addc_co_u32_e32 v55, vcc, 0, v63, vcc
	global_load_dwordx4 v[50:53], v[50:51], off
	s_nop 0
	global_load_dwordx4 v[54:57], v[54:55], off
	v_add_co_u32_e32 v58, vcc, s47, v62
	s_nop 1
	v_addc_co_u32_e32 v59, vcc, 0, v63, vcc
	global_load_dwordx4 v[58:61], v[58:59], off
	v_add_co_u32_e32 v62, vcc, s48, v62
	s_nop 1
	v_addc_co_u32_e32 v63, vcc, 0, v63, vcc
	global_load_dwordx4 v[62:65], v[62:63], off
	s_waitcnt vmcnt(15)
	ds_write2_b32 v73, v2, v3 offset1:1
	ds_write2_b32 v73, v4, v5 offset0:2 offset1:3
	s_waitcnt vmcnt(14)
	ds_write2_b32 v83, v6, v7 offset1:1
	ds_write2_b32 v84, v8, v9 offset1:1
	s_waitcnt vmcnt(13)
	ds_write2_b32 v85, v10, v11 offset1:1
	ds_write2_b32 v86, v12, v13 offset1:1
	s_waitcnt vmcnt(12)
	ds_write2_b32 v87, v14, v15 offset1:1
	ds_write2_b32 v88, v16, v17 offset1:1
	s_waitcnt vmcnt(11)
	ds_write2_b32 v89, v18, v19 offset1:1
	ds_write2_b32 v90, v20, v21 offset1:1
	s_waitcnt vmcnt(10)
	ds_write2_b32 v91, v22, v23 offset1:1
	ds_write2_b32 v92, v24, v25 offset1:1
	s_waitcnt vmcnt(9)
	ds_write2_b32 v93, v26, v27 offset1:1
	ds_write2_b32 v94, v28, v29 offset1:1
	s_waitcnt vmcnt(8)
	ds_write2_b32 v95, v30, v31 offset1:1
	ds_write2_b32 v96, v32, v33 offset1:1
	s_waitcnt vmcnt(7)
	ds_write2_b32 v97, v34, v35 offset1:1
	ds_write2_b32 v98, v36, v37 offset1:1
	s_waitcnt vmcnt(6)
	ds_write2_b32 v99, v38, v39 offset1:1
	ds_write2_b32 v100, v40, v41 offset1:1
	s_waitcnt vmcnt(5)
	ds_write2_b32 v101, v42, v43 offset1:1
	ds_write2_b32 v102, v44, v45 offset1:1
	s_waitcnt vmcnt(4)
	ds_write2_b32 v103, v46, v47 offset1:1
	ds_write2_b32 v104, v48, v49 offset1:1
	s_waitcnt vmcnt(3)
	ds_write2_b32 v105, v50, v51 offset1:1
	ds_write2_b32 v106, v52, v53 offset1:1
	s_waitcnt vmcnt(2)
	ds_write2_b32 v107, v54, v55 offset1:1
	ds_write2_b32 v108, v56, v57 offset1:1
	s_waitcnt vmcnt(1)
	ds_write2_b32 v109, v58, v59 offset1:1
	ds_write2_b32 v110, v60, v61 offset1:1
	s_waitcnt vmcnt(0)
	ds_write2_b32 v111, v62, v63 offset1:1
	ds_write2_b32 v112, v64, v65 offset1:1
	s_waitcnt lgkmcnt(0)
; #define LAS __attribute__((address_space(3)))
; __device__ __forceinline__ unsigned pk2(float lo, float hi) { return pg8::cvt_pk_bf16(lo, hi); }
; __device__ __forceinline__ void p0_transpose_item(const float* __restrict__ W, const float* __restrict__ gain, int K, int N, bf16* __restrict__ WT, int mode, LAS float* scr, int item, int lane) {
;     ...
;     for (int j = 0; j < 8; ++j) { const int n = (lane >> 3) + 8 * j; const LAS float* s = scr + (8 * c) * 65 + n;
;         v4u o; o.x = pk2(s[0 * 65], s[1 * 65]); o.y = pk2(s[2 * 65], s[3 * 65]); o.z = pk2(s[4 * 65], s[5 * 65]); o.w = pk2(s[6 * 65], s[7 * 65]);
;         *(v4u*)(WT + (size_t)(rowbase + n) * K + k0 + 8 * c) = o; }
;     asm volatile("s_waitcnt lgkmcnt(0)" ::: "memory");
	ds_read2_b32 v[150:151], v75 offset1:65
	ds_read2_b32 v[152:153], v75 offset0:130 offset1:195
	ds_read2_b32 v[154:155], v113 offset0:4 offset1:69
	ds_read2_b32 v[156:157], v113 offset0:134 offset1:199
	ds_read2_b32 v[158:159], v75 offset0:8 offset1:73
	ds_read2_b32 v[160:161], v75 offset0:138 offset1:203
	ds_read2_b32 v[162:163], v113 offset0:12 offset1:77
	ds_read2_b32 v[164:165], v113 offset0:142 offset1:207
	ds_read2_b32 v[166:167], v75 offset0:16 offset1:81
	ds_read2_b32 v[168:169], v75 offset0:146 offset1:211
	ds_read2_b32 v[170:171], v113 offset0:20 offset1:85
	ds_read2_b32 v[172:173], v113 offset0:150 offset1:215
	ds_read2_b32 v[174:175], v75 offset0:24 offset1:89
	ds_read2_b32 v[176:177], v75 offset0:154 offset1:219
	ds_read2_b32 v[178:179], v113 offset0:28 offset1:93
	ds_read2_b32 v[180:181], v113 offset0:158 offset1:223
	ds_read2_b32 v[182:183], v75 offset0:32 offset1:97
	ds_read2_b32 v[184:185], v75 offset0:162 offset1:227
	ds_read2_b32 v[186:187], v113 offset0:36 offset1:101
	ds_read2_b32 v[188:189], v113 offset0:166 offset1:231
	ds_read2_b32 v[190:191], v75 offset0:40 offset1:105
	ds_read2_b32 v[192:193], v75 offset0:170 offset1:235
	ds_read2_b32 v[194:195], v113 offset0:44 offset1:109
	ds_read2_b32 v[196:197], v113 offset0:174 offset1:239
	ds_read2_b32 v[198:199], v75 offset0:48 offset1:113
	ds_read2_b32 v[200:201], v75 offset0:178 offset1:243
	ds_read2_b32 v[202:203], v113 offset0:52 offset1:117
	ds_read2_b32 v[204:205], v113 offset0:182 offset1:247
	ds_read2_b32 v[206:207], v75 offset0:56 offset1:121
	ds_read2_b32 v[208:209], v75 offset0:186 offset1:251
	ds_read2_b32 v[210:211], v113 offset0:60 offset1:125
	ds_read2_b32 v[212:213], v113 offset0:190 offset1:255
	s_waitcnt lgkmcnt(15)
	v_cvt_pk_bf16_f32 v214, v150, v151
	v_lshl_add_u64 v[8:9], s[24:25], 0, v[68:69]
	v_or_b32_e32 v10, s21, v74
	s_waitcnt lgkmcnt(15)
	v_cvt_pk_bf16_f32 v215, v152, v153
	v_lshl_add_u64 v[8:9], v[8:9], 0, s[14:15]
	v_lshlrev_b32_e32 v10, 12, v10
	v_mov_b32_e32 v11, v67
	s_waitcnt lgkmcnt(15)
	v_cvt_pk_bf16_f32 v216, v154, v155
	s_waitcnt lgkmcnt(15)
	v_cvt_pk_bf16_f32 v217, v156, v157
	v_lshl_add_u64 v[10:11], v[8:9], 0, v[10:11]
	global_store_dwordx4 v[10:11], v[214:217], off
	v_or_b32_e32 v10, s21, v76
	v_lshlrev_b32_e32 v10, 12, v10
	s_waitcnt lgkmcnt(15)
	v_cvt_pk_bf16_f32 v218, v158, v159
	s_waitcnt lgkmcnt(15)
	v_cvt_pk_bf16_f32 v219, v160, v161
	v_mov_b32_e32 v11, v67
	s_waitcnt lgkmcnt(15)
	v_cvt_pk_bf16_f32 v220, v162, v163
	s_waitcnt lgkmcnt(15)
	v_cvt_pk_bf16_f32 v221, v164, v165
	v_lshl_add_u64 v[10:11], v[8:9], 0, v[10:11]
	global_store_dwordx4 v[10:11], v[218:221], off
	v_or_b32_e32 v10, s21, v77
	v_lshlrev_b32_e32 v10, 12, v10
	s_waitcnt lgkmcnt(15)
	v_cvt_pk_bf16_f32 v222, v166, v167
	s_waitcnt lgkmcnt(15)
	v_cvt_pk_bf16_f32 v223, v168, v169
	v_mov_b32_e32 v11, v67
	s_waitcnt lgkmcnt(15)
	v_cvt_pk_bf16_f32 v224, v170, v171
	s_waitcnt lgkmcnt(15)
	v_cvt_pk_bf16_f32 v225, v172, v173
	v_lshl_add_u64 v[10:11], v[8:9], 0, v[10:11]
	global_store_dwordx4 v[10:11], v[222:225], off
	v_or_b32_e32 v10, s21, v78
	v_lshlrev_b32_e32 v10, 12, v10
	s_waitcnt lgkmcnt(15)
	v_cvt_pk_bf16_f32 v226, v174, v175
	s_waitcnt lgkmcnt(15)
	v_cvt_pk_bf16_f32 v227, v176, v177
	v_mov_b32_e32 v11, v67
	s_waitcnt lgkmcnt(15)
	v_cvt_pk_bf16_f32 v228, v178, v179
	s_waitcnt lgkmcnt(15)
	v_cvt_pk_bf16_f32 v229, v180, v181
	v_lshl_add_u64 v[10:11], v[8:9], 0, v[10:11]
	global_store_dwordx4 v[10:11], v[226:229], off
	v_or_b32_e32 v10, s21, v79
	v_mov_b32_e32 v11, v67
	s_waitcnt lgkmcnt(15)
	v_cvt_pk_bf16_f32 v230, v182, v183
	s_waitcnt lgkmcnt(14)
	v_cvt_pk_bf16_f32 v231, v184, v185
	v_lshlrev_b32_e32 v10, 12, v10
	s_waitcnt lgkmcnt(13)
	v_cvt_pk_bf16_f32 v232, v186, v187
	s_waitcnt lgkmcnt(12)
	v_cvt_pk_bf16_f32 v233, v188, v189
	v_lshl_add_u64 v[10:11], v[8:9], 0, v[10:11]
	global_store_dwordx4 v[10:11], v[230:233], off
	v_or_b32_e32 v10, s21, v80
	v_mov_b32_e32 v11, v67
	s_waitcnt lgkmcnt(11)
	v_cvt_pk_bf16_f32 v234, v190, v191
	s_waitcnt lgkmcnt(10)
	v_cvt_pk_bf16_f32 v235, v192, v193
	v_lshlrev_b32_e32 v10, 12, v10
	s_waitcnt lgkmcnt(9)
	v_cvt_pk_bf16_f32 v236, v194, v195
	s_waitcnt lgkmcnt(8)
	v_cvt_pk_bf16_f32 v237, v196, v197
	v_lshl_add_u64 v[10:11], v[8:9], 0, v[10:11]
	global_store_dwordx4 v[10:11], v[234:237], off
	v_or_b32_e32 v10, s21, v81
	v_mov_b32_e32 v11, v67
	s_waitcnt lgkmcnt(7)
	v_cvt_pk_bf16_f32 v238, v198, v199
	s_waitcnt lgkmcnt(6)
	v_cvt_pk_bf16_f32 v239, v200, v201
	v_lshlrev_b32_e32 v10, 12, v10
	s_waitcnt lgkmcnt(5)
	v_cvt_pk_bf16_f32 v240, v202, v203
	s_waitcnt lgkmcnt(4)
	v_cvt_pk_bf16_f32 v241, v204, v205
	v_lshl_add_u64 v[10:11], v[8:9], 0, v[10:11]
	global_store_dwordx4 v[10:11], v[238:241], off
	v_mov_b32_e32 v11, v67
	s_waitcnt lgkmcnt(3)
	v_cvt_pk_bf16_f32 v242, v206, v207
	s_waitcnt lgkmcnt(2)
	v_cvt_pk_bf16_f32 v243, v208, v209
	s_waitcnt lgkmcnt(1)
	v_cvt_pk_bf16_f32 v244, v210, v211
	v_or_b32_e32 v5, s21, v82
	v_lshlrev_b32_e32 v10, 12, v5
	s_waitcnt lgkmcnt(0)
	v_cvt_pk_bf16_f32 v245, v212, v213
	v_lshl_add_u64 v[6:7], v[8:9], 0, v[10:11]
	global_store_dwordx4 v[6:7], v[242:245], off
	s_waitcnt lgkmcnt(0)

; #define LAS __attribute__((address_space(3)))
; __device__ __forceinline__ unsigned pk2(float lo, float hi) { return pg8::cvt_pk_bf16(lo, hi); }
; __device__ __forceinline__ void p0_transpose_item(const float* __restrict__ W, const float* __restrict__ gain, int K, int N, bf16* __restrict__ WT, int mode, LAS float* scr, int item, int lane) {
;     ...
;     for (int i = 0; i < 16; ++i) { LAS float* d = scr + (4 * i + lr) * 65 + lc4; d[0] = v[i].x; d[1] = v[i].y; d[2] = v[i].z; d[3] = v[i].w; }
;     asm volatile("s_waitcnt lgkmcnt(0)" ::: "memory");
;     const int c = lane & 7;
;     const int rowbase = mode == 0 ? n0 : (((n0 >> 7) << 8) + (n0 & 127) + (mode == 2 ? 128 : 0));
; #pragma unroll
;     for (int j = 0; j < 8; ++j) { const int n = (lane >> 3) + 8 * j; const LAS float* s = scr + (8 * c) * 65 + n;
;         v4u o; o.x = pk2(s[0 * 65], s[1 * 65]); o.y = pk2(s[2 * 65], s[3 * 65]); o.z = pk2(s[4 * 65], s[5 * 65]); o.w = pk2(s[6 * 65], s[7 * 65]);
;         *(v4u*)(WT + (size_t)(rowbase + n) * K + k0 + 8 * c) = o; }
.LBB0_28:
	s_lshl_b32 s24, s55, 6
	s_and_b32 s21, 0xffff, s21
	s_waitcnt vmcnt(15)
	ds_write2_b32 v73, v6, v7 offset1:1
	ds_write2_b32 v73, v8, v9 offset0:2 offset1:3
	s_waitcnt vmcnt(14)
	ds_write2_b32 v83, v2, v3 offset1:1
	ds_write2_b32 v84, v4, v5 offset1:1
	s_waitcnt vmcnt(13)
	ds_write2_b32 v85, v14, v15 offset1:1
	ds_write2_b32 v86, v16, v17 offset1:1
	s_waitcnt vmcnt(12)
	ds_write2_b32 v87, v10, v11 offset1:1
	ds_write2_b32 v88, v12, v13 offset1:1
	s_waitcnt vmcnt(11)
	ds_write2_b32 v89, v22, v23 offset1:1
	ds_write2_b32 v90, v24, v25 offset1:1
	s_waitcnt vmcnt(10)
	ds_write2_b32 v91, v18, v19 offset1:1
	ds_write2_b32 v92, v20, v21 offset1:1
	s_waitcnt vmcnt(9)
	ds_write2_b32 v93, v30, v31 offset1:1
	ds_write2_b32 v94, v32, v33 offset1:1
	s_waitcnt vmcnt(8)
	ds_write2_b32 v95, v26, v27 offset1:1
	ds_write2_b32 v96, v28, v29 offset1:1
	s_waitcnt vmcnt(7)
	ds_write2_b32 v97, v38, v39 offset1:1
	ds_write2_b32 v98, v40, v41 offset1:1
	s_waitcnt vmcnt(6)
	ds_write2_b32 v99, v34, v35 offset1:1
	ds_write2_b32 v100, v36, v37 offset1:1
	s_waitcnt vmcnt(5)
	ds_write2_b32 v101, v46, v47 offset1:1
	ds_write2_b32 v102, v48, v49 offset1:1
	s_waitcnt vmcnt(4)
	ds_write2_b32 v103, v42, v43 offset1:1
	ds_write2_b32 v104, v44, v45 offset1:1
	s_waitcnt vmcnt(3)
	ds_write2_b32 v105, v54, v55 offset1:1
	ds_write2_b32 v106, v56, v57 offset1:1
	s_waitcnt vmcnt(2)
	ds_write2_b32 v107, v50, v51 offset1:1
	ds_write2_b32 v108, v52, v53 offset1:1
	s_waitcnt vmcnt(1)
	ds_write2_b32 v109, v62, v63 offset1:1
	ds_write2_b32 v110, v64, v65 offset1:1
	s_waitcnt vmcnt(0)
	ds_write2_b32 v111, v58, v59 offset1:1
	ds_write2_b32 v112, v60, v61 offset1:1
	s_and_b32 s24, 0xffff, s24
	s_lshl_b32 s21, s21, 1
	s_waitcnt lgkmcnt(0)
	s_add_u32 s56, s52, s21
	ds_read2_b32 v[150:151], v75 offset1:65
	ds_read2_b32 v[152:153], v75 offset0:130 offset1:195
	ds_read2_b32 v[154:155], v113 offset0:4 offset1:69
	ds_read2_b32 v[156:157], v113 offset0:134 offset1:199
	ds_read2_b32 v[158:159], v75 offset0:8 offset1:73
	ds_read2_b32 v[160:161], v75 offset0:138 offset1:203
	ds_read2_b32 v[162:163], v113 offset0:12 offset1:77
	ds_read2_b32 v[164:165], v113 offset0:142 offset1:207
	ds_read2_b32 v[166:167], v75 offset0:16 offset1:81
	ds_read2_b32 v[168:169], v75 offset0:146 offset1:211
	ds_read2_b32 v[170:171], v113 offset0:20 offset1:85
	ds_read2_b32 v[172:173], v113 offset0:150 offset1:215
	ds_read2_b32 v[174:175], v75 offset0:24 offset1:89
	ds_read2_b32 v[176:177], v75 offset0:154 offset1:219
	ds_read2_b32 v[178:179], v113 offset0:28 offset1:93
	ds_read2_b32 v[180:181], v113 offset0:158 offset1:223
	ds_read2_b32 v[182:183], v75 offset0:32 offset1:97
	ds_read2_b32 v[184:185], v75 offset0:162 offset1:227
	ds_read2_b32 v[186:187], v113 offset0:36 offset1:101
	ds_read2_b32 v[188:189], v113 offset0:166 offset1:231
	ds_read2_b32 v[190:191], v75 offset0:40 offset1:105
	ds_read2_b32 v[192:193], v75 offset0:170 offset1:235
	ds_read2_b32 v[194:195], v113 offset0:44 offset1:109
	ds_read2_b32 v[196:197], v113 offset0:174 offset1:239
	ds_read2_b32 v[198:199], v75 offset0:48 offset1:113
	ds_read2_b32 v[200:201], v75 offset0:178 offset1:243
	ds_read2_b32 v[202:203], v113 offset0:52 offset1:117
	ds_read2_b32 v[204:205], v113 offset0:182 offset1:247
	ds_read2_b32 v[206:207], v75 offset0:56 offset1:121
	ds_read2_b32 v[208:209], v75 offset0:186 offset1:251
	ds_read2_b32 v[210:211], v113 offset0:60 offset1:125
	ds_read2_b32 v[212:213], v113 offset0:190 offset1:255
	s_addc_u32 s57, s53, 0
	v_mov_b32_e32 v69, v67
	s_waitcnt lgkmcnt(15)
	v_cvt_pk_bf16_f32 v214, v150, v151
	v_lshl_add_u64 v[8:9], s[56:57], 0, v[68:69]
	v_or_b32_e32 v10, s24, v74
	s_waitcnt lgkmcnt(15)
; #define LAS __attribute__((address_space(3)))
; __device__ __forceinline__ unsigned pk2(float lo, float hi) { return pg8::cvt_pk_bf16(lo, hi); }
; __device__ __forceinline__ void p0_transpose_item(const float* __restrict__ W, const float* __restrict__ gain, int K, int N, bf16* __restrict__ WT, int mode, LAS float* scr, int item, int lane) {
;     ...
;     for (int j = 0; j < 8; ++j) { const int n = (lane >> 3) + 8 * j; const LAS float* s = scr + (8 * c) * 65 + n;
;         v4u o; o.x = pk2(s[0 * 65], s[1 * 65]); o.y = pk2(s[2 * 65], s[3 * 65]); o.z = pk2(s[4 * 65], s[5 * 65]); o.w = pk2(s[6 * 65], s[7 * 65]);
;         *(v4u*)(WT + (size_t)(rowbase + n) * K + k0 + 8 * c) = o; }
;     asm volatile("s_waitcnt lgkmcnt(0)" ::: "memory");
	v_cvt_pk_bf16_f32 v215, v152, v153
	v_lshl_add_u64 v[8:9], v[8:9], 0, s[16:17]
	v_lshlrev_b32_e32 v10, 12, v10
	v_mov_b32_e32 v11, v67
	s_waitcnt lgkmcnt(15)
	v_cvt_pk_bf16_f32 v216, v154, v155
	s_waitcnt lgkmcnt(15)
	v_cvt_pk_bf16_f32 v217, v156, v157
	v_lshl_add_u64 v[10:11], v[8:9], 0, v[10:11]
	global_store_dwordx4 v[10:11], v[214:217], off
	v_or_b32_e32 v10, s24, v76
	v_lshlrev_b32_e32 v10, 12, v10
	s_waitcnt lgkmcnt(15)
	v_cvt_pk_bf16_f32 v218, v158, v159
	s_waitcnt lgkmcnt(15)
	v_cvt_pk_bf16_f32 v219, v160, v161
	v_mov_b32_e32 v11, v67
	s_waitcnt lgkmcnt(15)
	v_cvt_pk_bf16_f32 v220, v162, v163
	s_waitcnt lgkmcnt(15)
	v_cvt_pk_bf16_f32 v221, v164, v165
	v_lshl_add_u64 v[10:11], v[8:9], 0, v[10:11]
	global_store_dwordx4 v[10:11], v[218:221], off
	v_or_b32_e32 v10, s24, v77
	v_lshlrev_b32_e32 v10, 12, v10
	s_waitcnt lgkmcnt(15)
	v_cvt_pk_bf16_f32 v222, v166, v167
	s_waitcnt lgkmcnt(15)
	v_cvt_pk_bf16_f32 v223, v168, v169
	v_mov_b32_e32 v11, v67
	s_waitcnt lgkmcnt(15)
	v_cvt_pk_bf16_f32 v224, v170, v171
	s_waitcnt lgkmcnt(15)
	v_cvt_pk_bf16_f32 v225, v172, v173
	v_lshl_add_u64 v[10:11], v[8:9], 0, v[10:11]
	global_store_dwordx4 v[10:11], v[222:225], off
	v_or_b32_e32 v10, s24, v78
	v_lshlrev_b32_e32 v10, 12, v10
	s_waitcnt lgkmcnt(15)
	v_cvt_pk_bf16_f32 v226, v174, v175
	s_waitcnt lgkmcnt(15)
	v_cvt_pk_bf16_f32 v227, v176, v177
	v_mov_b32_e32 v11, v67
	s_waitcnt lgkmcnt(15)
	v_cvt_pk_bf16_f32 v228, v178, v179
	s_waitcnt lgkmcnt(15)
	v_cvt_pk_bf16_f32 v229, v180, v181
	v_lshl_add_u64 v[10:11], v[8:9], 0, v[10:11]
	global_store_dwordx4 v[10:11], v[226:229], off
	v_or_b32_e32 v10, s24, v79
	v_lshlrev_b32_e32 v10, 12, v10
	s_waitcnt lgkmcnt(15)
	v_cvt_pk_bf16_f32 v230, v182, v183
	s_waitcnt lgkmcnt(14)
	v_cvt_pk_bf16_f32 v231, v184, v185
	v_mov_b32_e32 v11, v67
	s_waitcnt lgkmcnt(13)
	v_cvt_pk_bf16_f32 v232, v186, v187
	s_waitcnt lgkmcnt(12)
	v_cvt_pk_bf16_f32 v233, v188, v189
	v_lshl_add_u64 v[10:11], v[8:9], 0, v[10:11]
	global_store_dwordx4 v[10:11], v[230:233], off
	v_or_b32_e32 v10, s24, v80
	v_mov_b32_e32 v11, v67
	s_waitcnt lgkmcnt(11)
	v_cvt_pk_bf16_f32 v234, v190, v191
	s_waitcnt lgkmcnt(10)
	v_cvt_pk_bf16_f32 v235, v192, v193
	v_lshlrev_b32_e32 v10, 12, v10
	s_waitcnt lgkmcnt(9)
	v_cvt_pk_bf16_f32 v236, v194, v195
	s_waitcnt lgkmcnt(8)
	v_cvt_pk_bf16_f32 v237, v196, v197
	v_lshl_add_u64 v[10:11], v[8:9], 0, v[10:11]
	global_store_dwordx4 v[10:11], v[234:237], off
	v_or_b32_e32 v10, s24, v81
	v_mov_b32_e32 v11, v67
	s_waitcnt lgkmcnt(7)
	v_cvt_pk_bf16_f32 v238, v198, v199
	s_waitcnt lgkmcnt(6)
	v_cvt_pk_bf16_f32 v239, v200, v201
	v_lshlrev_b32_e32 v10, 12, v10
	s_waitcnt lgkmcnt(5)
	v_cvt_pk_bf16_f32 v240, v202, v203
	s_waitcnt lgkmcnt(4)
	v_cvt_pk_bf16_f32 v241, v204, v205
	v_lshl_add_u64 v[10:11], v[8:9], 0, v[10:11]
	global_store_dwordx4 v[10:11], v[238:241], off
	v_mov_b32_e32 v11, v67
	v_readlane_b32 s76, v254, 21
	s_waitcnt lgkmcnt(3)
	v_cvt_pk_bf16_f32 v242, v206, v207
	s_waitcnt lgkmcnt(2)
	v_cvt_pk_bf16_f32 v243, v208, v209
	s_waitcnt lgkmcnt(1)
	v_cvt_pk_bf16_f32 v244, v210, v211
	v_or_b32_e32 v5, s24, v82
	v_lshlrev_b32_e32 v10, 12, v5
	s_waitcnt lgkmcnt(0)
	v_cvt_pk_bf16_f32 v245, v212, v213
	v_lshl_add_u64 v[6:7], v[8:9], 0, v[10:11]
	global_store_dwordx4 v[6:7], v[242:245], off
	s_waitcnt lgkmcnt(0)
	v_readlane_b32 s77, v254, 22
	v_readlane_b32 s78, v254, 23
	v_readlane_b32 s79, v254, 24
	v_readlane_b32 s80, v254, 25
	v_readlane_b32 s81, v254, 26
	v_readlane_b32 s82, v254, 27
	v_readlane_b32 s83, v254, 28
	v_readlane_b32 s84, v254, 29
	v_readlane_b32 s85, v254, 30
	v_readlane_b32 s86, v254, 31
	v_readlane_b32 s87, v254, 32
	v_readlane_b32 s88, v254, 33
	v_readlane_b32 s89, v254, 34
	v_readlane_b32 s90, v254, 35
	v_readlane_b32 s91, v254, 36

; #define LAS __attribute__((address_space(3)))
; __device__ __forceinline__ void p0_transpose_item(const float* __restrict__ W, const float* __restrict__ gain, int K, int N, bf16* __restrict__ WT, int mode, LAS float* scr, int item, int lane) {
;     const int nblk = N / 64, kb = item / nblk, nb = item % nblk, k0 = 64 * kb, n0 = 64 * nb, lr = lane >> 4, lc4 = (lane & 15) * 4;
;     f32x4 v[16];
; #pragma unroll
;     for (int i = 0; i < 16; ++i) v[i] = *(const f32x4*)(W + (size_t)(k0 + 4 * i + lr) * N + n0 + lc4);
;     if (gain) {
; #pragma unroll
;         for (int i = 0; i < 16; ++i) v[i] = v[i] * gain[k0 + 4 * i + lr]; }
; #pragma unroll
;     for (int i = 0; i < 16; ++i) { LAS float* d = scr + (4 * i + lr) * 65 + lc4; d[0] = v[i].x; d[1] = v[i].y; d[2] = v[i].z; d[3] = v[i].w; }
;     asm volatile("s_waitcnt lgkmcnt(0)" ::: "memory");
; __device__ __forceinline__ void p0_prologue(const Args& a, LAS unsigned char* lds, int gw, int NGW, int lane, int wave) {
;     ...
;         if (r < I_A) { p0_transpose_item(a.in[2] + og, a.in[1] + l * DM, DM, DFF, (bf16*)(wl + W_GU1), 1, scr, r, lane); continue; } r -= I_A;
;         if (r < I_A) { p0_transpose_item(a.in[3] + og, a.in[1] + l * DM, DM, DFF, (bf16*)(wl + W_GU1), 2, scr, r, lane); continue; } r -= I_A;
;         if (r < I_D) { p0_transpose_item(a.in[4] + og, nullptr, DFF, DM, (bf16*)(wl + W_D1), 0, scr, r, lane); continue; } r -= I_D;
;         if (r < I_IN) { p0_transpose_item(a.in[6] + (size_t)l * DM * DIN, a.in[5] + l * DM, DM, DIN, (bf16*)(wl + W_IN), 0, scr, r, lane); continue; } r -= I_IN;
;         if (r < I_OUT) { p0_transpose_item(a.in[10] + (size_t)l * DM * DM, nullptr, DM, DM, (bf16*)(wl + W_OUT), 0, scr, r, lane); continue; } r -= I_OUT;
;         if (r < I_A) { p0_transpose_item(a.in[12] + og, a.in[11] + l * DM, DM, DFF, (bf16*)(wl + W_GU2), 1, scr, r, lane); continue; } r -= I_A;
;         if (r < I_A) { p0_transpose_item(a.in[13] + og, a.in[11] + l * DM, DM, DFF, (bf16*)(wl + W_GU2), 2, scr, r, lane); continue; } r -= I_A;
;         p0_transpose_item(a.in[14] + og, nullptr, DFF, DM, (bf16*)(wl + W_D2), 0, scr, r, lane);
.LBB0_30:
	s_andn2_b64 vcc, exec, s[24:25]
	s_cbranch_vccnz .LBB0_32
	v_readlane_b32 s76, v254, 0
	s_lshl_b64 s[24:25], s[22:23], 2
	v_readlane_b32 s84, v254, 8
	v_readlane_b32 s85, v254, 9
	s_add_u32 s24, s84, s24
	s_mul_i32 s21, s20, 0xffff6000
	s_addc_u32 s25, s85, s25
	s_add_i32 s21, s31, s21
	s_and_b32 s55, s21, 0x1ffc0
	s_and_b32 s21, s29, 0x7c0
	s_lshl_b32 s56, s21, 2
	s_add_u32 s24, s24, s56
	v_or_b32_e32 v4, s55, v72
	s_addc_u32 s25, s25, 0
	v_lshl_add_u64 v[2:3], s[24:25], 0, v[66:67]
	v_lshlrev_b32_e32 v4, 13, v4
	v_mov_b32_e32 v5, v67
	v_lshl_add_u64 v[62:63], v[2:3], 0, v[4:5]
	v_add_co_u32_e32 v6, vcc, s34, v62
	s_lshl_b32 s24, s55, 1
	s_nop 0
	v_addc_co_u32_e32 v7, vcc, 0, v63, vcc
	v_add_co_u32_e32 v10, vcc, s35, v62
	global_load_dwordx4 v[2:5], v[62:63], off
	s_nop 0
	global_load_dwordx4 v[6:9], v[6:7], off
	v_addc_co_u32_e32 v11, vcc, 0, v63, vcc
	v_add_co_u32_e32 v14, vcc, s36, v62
	s_add_u32 s24, s52, s24
	s_nop 0
	v_addc_co_u32_e32 v15, vcc, 0, v63, vcc
	v_add_co_u32_e32 v18, vcc, s37, v62
	global_load_dwordx4 v[10:13], v[10:11], off
	s_nop 0
	global_load_dwordx4 v[14:17], v[14:15], off
	v_addc_co_u32_e32 v19, vcc, 0, v63, vcc
	v_add_co_u32_e32 v22, vcc, s38, v62
	s_addc_u32 s25, s53, 0
	s_nop 0
	v_addc_co_u32_e32 v23, vcc, 0, v63, vcc
	v_add_co_u32_e32 v26, vcc, s39, v62
	global_load_dwordx4 v[18:21], v[18:19], off
	s_nop 0
	global_load_dwordx4 v[22:25], v[22:23], off
	v_addc_co_u32_e32 v27, vcc, 0, v63, vcc
	v_add_co_u32_e32 v30, vcc, s40, v62
	v_mov_b32_e32 v69, v67
	s_nop 0
	v_addc_co_u32_e32 v31, vcc, 0, v63, vcc
	v_add_co_u32_e32 v34, vcc, s41, v62
	global_load_dwordx4 v[26:29], v[26:27], off
	s_nop 0
	global_load_dwordx4 v[30:33], v[30:31], off
	v_addc_co_u32_e32 v35, vcc, 0, v63, vcc
	v_add_co_u32_e32 v38, vcc, s42, v62
	v_readlane_b32 s77, v254, 1
	s_nop 0
	v_addc_co_u32_e32 v39, vcc, 0, v63, vcc
	v_add_co_u32_e32 v42, vcc, s43, v62
	global_load_dwordx4 v[34:37], v[34:35], off
	s_nop 0
	global_load_dwordx4 v[38:41], v[38:39], off
	v_addc_co_u32_e32 v43, vcc, 0, v63, vcc
	v_add_co_u32_e32 v46, vcc, s44, v62
	v_readlane_b32 s78, v254, 2
	s_nop 0
	v_addc_co_u32_e32 v47, vcc, 0, v63, vcc
	v_add_co_u32_e32 v50, vcc, s45, v62
	global_load_dwordx4 v[42:45], v[42:43], off
	s_nop 0
	global_load_dwordx4 v[46:49], v[46:47], off
	v_addc_co_u32_e32 v51, vcc, 0, v63, vcc
	v_add_co_u32_e32 v54, vcc, s46, v62
	v_readlane_b32 s79, v254, 3
	s_nop 0
	v_addc_co_u32_e32 v55, vcc, 0, v63, vcc
	global_load_dwordx4 v[50:53], v[50:51], off
	s_nop 0
	global_load_dwordx4 v[54:57], v[54:55], off
	v_add_co_u32_e32 v58, vcc, s47, v62
	v_readlane_b32 s80, v254, 4
	s_nop 0
	v_addc_co_u32_e32 v59, vcc, 0, v63, vcc
	global_load_dwordx4 v[58:61], v[58:59], off
	v_add_co_u32_e32 v62, vcc, s48, v62
	v_readlane_b32 s81, v254, 5
	s_nop 0
	v_addc_co_u32_e32 v63, vcc, 0, v63, vcc
	global_load_dwordx4 v[62:65], v[62:63], off
	v_readlane_b32 s82, v254, 6
	v_readlane_b32 s83, v254, 7
	v_readlane_b32 s86, v254, 10
	v_readlane_b32 s87, v254, 11
	v_readlane_b32 s88, v254, 12
	v_readlane_b32 s89, v254, 13
	v_readlane_b32 s90, v254, 14
	v_readlane_b32 s91, v254, 15
	v_readlane_b32 s76, v254, 21
	v_readlane_b32 s77, v254, 22
	v_readlane_b32 s78, v254, 23
	v_readlane_b32 s79, v254, 24
	v_readlane_b32 s80, v254, 25
	v_readlane_b32 s81, v254, 26
	v_readlane_b32 s82, v254, 27
	v_readlane_b32 s83, v254, 28
	v_readlane_b32 s84, v254, 29
	v_readlane_b32 s85, v254, 30
	v_readlane_b32 s86, v254, 31
	v_readlane_b32 s87, v254, 32
	s_waitcnt vmcnt(15)
	ds_write2_b32 v73, v2, v3 offset1:1
	ds_write2_b32 v73, v4, v5 offset0:2 offset1:3
	s_waitcnt vmcnt(14)
	ds_write2_b32 v83, v6, v7 offset1:1
	ds_write2_b32 v84, v8, v9 offset1:1
	s_waitcnt vmcnt(13)
	ds_write2_b32 v85, v10, v11 offset1:1
	ds_write2_b32 v86, v12, v13 offset1:1
	s_waitcnt vmcnt(12)
	ds_write2_b32 v87, v14, v15 offset1:1
	ds_write2_b32 v88, v16, v17 offset1:1
	s_waitcnt vmcnt(11)
	ds_write2_b32 v89, v18, v19 offset1:1
	ds_write2_b32 v90, v20, v21 offset1:1
	s_waitcnt vmcnt(10)
	ds_write2_b32 v91, v22, v23 offset1:1
	ds_write2_b32 v92, v24, v25 offset1:1
	s_waitcnt vmcnt(9)
	ds_write2_b32 v93, v26, v27 offset1:1
	ds_write2_b32 v94, v28, v29 offset1:1
	s_waitcnt vmcnt(8)
	ds_write2_b32 v95, v30, v31 offset1:1
	ds_write2_b32 v96, v32, v33 offset1:1
	s_waitcnt vmcnt(7)
	ds_write2_b32 v97, v34, v35 offset1:1
	ds_write2_b32 v98, v36, v37 offset1:1
	s_waitcnt vmcnt(6)
	ds_write2_b32 v99, v38, v39 offset1:1
	ds_write2_b32 v100, v40, v41 offset1:1
	s_waitcnt vmcnt(5)
	ds_write2_b32 v101, v42, v43 offset1:1
	ds_write2_b32 v102, v44, v45 offset1:1
	s_waitcnt vmcnt(4)
	ds_write2_b32 v103, v46, v47 offset1:1
	ds_write2_b32 v104, v48, v49 offset1:1
	s_waitcnt vmcnt(3)
	ds_write2_b32 v105, v50, v51 offset1:1
	ds_write2_b32 v106, v52, v53 offset1:1
	s_waitcnt vmcnt(2)
	ds_write2_b32 v107, v54, v55 offset1:1
	ds_write2_b32 v108, v56, v57 offset1:1
	s_waitcnt vmcnt(1)
	ds_write2_b32 v109, v58, v59 offset1:1
	ds_write2_b32 v110, v60, v61 offset1:1
	s_waitcnt vmcnt(0)
	ds_write2_b32 v111, v62, v63 offset1:1
	ds_write2_b32 v112, v64, v65 offset1:1
	s_waitcnt lgkmcnt(0)
; #define LAS __attribute__((address_space(3)))
; __device__ __forceinline__ unsigned pk2(float lo, float hi) { return pg8::cvt_pk_bf16(lo, hi); }
; __device__ __forceinline__ void p0_transpose_item(const float* __restrict__ W, const float* __restrict__ gain, int K, int N, bf16* __restrict__ WT, int mode, LAS float* scr, int item, int lane) {
;     ...
;     for (int j = 0; j < 8; ++j) { const int n = (lane >> 3) + 8 * j; const LAS float* s = scr + (8 * c) * 65 + n;
;         v4u o; o.x = pk2(s[0 * 65], s[1 * 65]); o.y = pk2(s[2 * 65], s[3 * 65]); o.z = pk2(s[4 * 65], s[5 * 65]); o.w = pk2(s[6 * 65], s[7 * 65]);
;         *(v4u*)(WT + (size_t)(rowbase + n) * K + k0 + 8 * c) = o; }
;     asm volatile("s_waitcnt lgkmcnt(0)" ::: "memory");
	ds_read2_b32 v[150:151], v75 offset1:65
	ds_read2_b32 v[152:153], v75 offset0:130 offset1:195
	ds_read2_b32 v[154:155], v113 offset0:4 offset1:69
	ds_read2_b32 v[156:157], v113 offset0:134 offset1:199
	ds_read2_b32 v[158:159], v75 offset0:8 offset1:73
	ds_read2_b32 v[160:161], v75 offset0:138 offset1:203
	ds_read2_b32 v[162:163], v113 offset0:12 offset1:77
	ds_read2_b32 v[164:165], v113 offset0:142 offset1:207
	ds_read2_b32 v[166:167], v75 offset0:16 offset1:81
	ds_read2_b32 v[168:169], v75 offset0:146 offset1:211
	ds_read2_b32 v[170:171], v113 offset0:20 offset1:85
	ds_read2_b32 v[172:173], v113 offset0:150 offset1:215
	ds_read2_b32 v[174:175], v75 offset0:24 offset1:89
	ds_read2_b32 v[176:177], v75 offset0:154 offset1:219
	ds_read2_b32 v[178:179], v113 offset0:28 offset1:93
	ds_read2_b32 v[180:181], v113 offset0:158 offset1:223
	ds_read2_b32 v[182:183], v75 offset0:32 offset1:97
	ds_read2_b32 v[184:185], v75 offset0:162 offset1:227
	ds_read2_b32 v[186:187], v113 offset0:36 offset1:101
	ds_read2_b32 v[188:189], v113 offset0:166 offset1:231
	ds_read2_b32 v[190:191], v75 offset0:40 offset1:105
	ds_read2_b32 v[192:193], v75 offset0:170 offset1:235
	ds_read2_b32 v[194:195], v113 offset0:44 offset1:109
	ds_read2_b32 v[196:197], v113 offset0:174 offset1:239
	ds_read2_b32 v[198:199], v75 offset0:48 offset1:113
	ds_read2_b32 v[200:201], v75 offset0:178 offset1:243
	ds_read2_b32 v[202:203], v113 offset0:52 offset1:117
	ds_read2_b32 v[204:205], v113 offset0:182 offset1:247
	ds_read2_b32 v[206:207], v75 offset0:56 offset1:121
	ds_read2_b32 v[208:209], v75 offset0:186 offset1:251
	ds_read2_b32 v[210:211], v113 offset0:60 offset1:125
	ds_read2_b32 v[212:213], v113 offset0:190 offset1:255
	s_waitcnt lgkmcnt(15)
	v_cvt_pk_bf16_f32 v214, v150, v151
	s_waitcnt lgkmcnt(15)
	v_cvt_pk_bf16_f32 v215, v152, v153
	s_waitcnt lgkmcnt(15)
	v_cvt_pk_bf16_f32 v216, v154, v155
	s_waitcnt lgkmcnt(15)
	v_cvt_pk_bf16_f32 v217, v156, v157
	v_or_b32_e32 v6, s21, v74
	v_lshl_add_u64 v[8:9], s[24:25], 0, v[68:69]
	v_mul_u32_u24_e32 v10, 0x1600, v6
	v_lshl_add_u64 v[8:9], v[8:9], 0, s[18:19]
	v_lshlrev_b32_e32 v10, 1, v10
	v_mov_b32_e32 v11, v67
	v_lshl_add_u64 v[10:11], v[8:9], 0, v[10:11]
	global_store_dwordx4 v[10:11], v[214:217], off
	v_mov_b32_e32 v11, v67
	v_readlane_b32 s88, v254, 33
	s_waitcnt lgkmcnt(15)
	v_cvt_pk_bf16_f32 v218, v158, v159
	s_waitcnt lgkmcnt(15)
	v_cvt_pk_bf16_f32 v219, v160, v161
	s_waitcnt lgkmcnt(15)
	v_cvt_pk_bf16_f32 v220, v162, v163
	s_waitcnt lgkmcnt(15)
	v_cvt_pk_bf16_f32 v221, v164, v165
	v_or_b32_e32 v6, s21, v76
	v_mul_u32_u24_e32 v10, 0x1600, v6
	v_lshlrev_b32_e32 v10, 1, v10
	v_lshl_add_u64 v[10:11], v[8:9], 0, v[10:11]
	global_store_dwordx4 v[10:11], v[218:221], off
	v_mov_b32_e32 v11, v67
	v_readlane_b32 s89, v254, 34
	s_waitcnt lgkmcnt(15)
	v_cvt_pk_bf16_f32 v222, v166, v167
	s_waitcnt lgkmcnt(15)
	v_cvt_pk_bf16_f32 v223, v168, v169
	s_waitcnt lgkmcnt(15)
	v_cvt_pk_bf16_f32 v224, v170, v171
	s_waitcnt lgkmcnt(15)
	v_cvt_pk_bf16_f32 v225, v172, v173
	v_or_b32_e32 v6, s21, v77
	v_mul_u32_u24_e32 v10, 0x1600, v6
	v_lshlrev_b32_e32 v10, 1, v10
	v_lshl_add_u64 v[10:11], v[8:9], 0, v[10:11]
	global_store_dwordx4 v[10:11], v[222:225], off
	v_mov_b32_e32 v11, v67
	v_readlane_b32 s90, v254, 35
	s_waitcnt lgkmcnt(15)
	v_cvt_pk_bf16_f32 v226, v174, v175
	s_waitcnt lgkmcnt(15)
	v_cvt_pk_bf16_f32 v227, v176, v177
	s_waitcnt lgkmcnt(15)
	v_cvt_pk_bf16_f32 v228, v178, v179
	s_waitcnt lgkmcnt(15)
	v_cvt_pk_bf16_f32 v229, v180, v181
	v_or_b32_e32 v6, s21, v78
	v_mul_u32_u24_e32 v10, 0x1600, v6
	v_lshlrev_b32_e32 v10, 1, v10
	v_lshl_add_u64 v[10:11], v[8:9], 0, v[10:11]
	global_store_dwordx4 v[10:11], v[226:229], off
	v_mov_b32_e32 v11, v67
	v_readlane_b32 s91, v254, 36
	s_waitcnt lgkmcnt(15)
	v_cvt_pk_bf16_f32 v230, v182, v183
	s_waitcnt lgkmcnt(14)
	v_cvt_pk_bf16_f32 v231, v184, v185
	s_waitcnt lgkmcnt(13)
	v_cvt_pk_bf16_f32 v232, v186, v187
	s_waitcnt lgkmcnt(12)
	v_cvt_pk_bf16_f32 v233, v188, v189
	v_or_b32_e32 v6, s21, v79
	v_mul_u32_u24_e32 v10, 0x1600, v6
	v_lshlrev_b32_e32 v10, 1, v10
	v_lshl_add_u64 v[10:11], v[8:9], 0, v[10:11]
	global_store_dwordx4 v[10:11], v[230:233], off
	v_or_b32_e32 v10, s21, v80
	v_mul_u32_u24_e32 v10, 0x1600, v10
	s_waitcnt lgkmcnt(11)
	v_cvt_pk_bf16_f32 v234, v190, v191
	v_mov_b32_e32 v11, v67
	v_lshlrev_b32_e32 v10, 1, v10
	s_waitcnt lgkmcnt(10)
	v_cvt_pk_bf16_f32 v235, v192, v193
	v_lshl_add_u64 v[10:11], v[8:9], 0, v[10:11]
	s_waitcnt lgkmcnt(9)
	v_cvt_pk_bf16_f32 v236, v194, v195
	s_waitcnt lgkmcnt(8)
	v_cvt_pk_bf16_f32 v237, v196, v197
	global_store_dwordx4 v[10:11], v[234:237], off
	v_or_b32_e32 v10, s21, v81
	s_waitcnt lgkmcnt(7)
	v_cvt_pk_bf16_f32 v238, v198, v199
	v_mul_u32_u24_e32 v10, 0x1600, v10
	s_waitcnt lgkmcnt(6)
	v_cvt_pk_bf16_f32 v239, v200, v201
	v_mov_b32_e32 v11, v67
	v_lshlrev_b32_e32 v10, 1, v10
	s_waitcnt lgkmcnt(5)
	v_cvt_pk_bf16_f32 v240, v202, v203
	s_waitcnt lgkmcnt(4)
	v_cvt_pk_bf16_f32 v241, v204, v205
	v_lshl_add_u64 v[10:11], v[8:9], 0, v[10:11]
	global_store_dwordx4 v[10:11], v[238:241], off
	v_mov_b32_e32 v11, v67
	s_waitcnt lgkmcnt(3)
	v_cvt_pk_bf16_f32 v242, v206, v207
	s_waitcnt lgkmcnt(2)
	v_cvt_pk_bf16_f32 v243, v208, v209
	s_waitcnt lgkmcnt(1)
	v_cvt_pk_bf16_f32 v244, v210, v211
	v_or_b32_e32 v5, s21, v82
	v_mul_u32_u24_e32 v5, 0x1600, v5
	v_lshlrev_b32_e32 v10, 1, v5
	s_waitcnt lgkmcnt(0)
	v_cvt_pk_bf16_f32 v245, v212, v213
	v_lshl_add_u64 v[6:7], v[8:9], 0, v[10:11]
	global_store_dwordx4 v[6:7], v[242:245], off
	s_waitcnt lgkmcnt(0)

; #define LAS __attribute__((address_space(3)))
; __device__ __forceinline__ unsigned pk2(float lo, float hi) { return pg8::cvt_pk_bf16(lo, hi); }
; __device__ __forceinline__ void p0_transpose_item(const float* __restrict__ W, const float* __restrict__ gain, int K, int N, bf16* __restrict__ WT, int mode, LAS float* scr, int item, int lane) {
;     ...
;     for (int i = 0; i < 16; ++i) { LAS float* d = scr + (4 * i + lr) * 65 + lc4; d[0] = v[i].x; d[1] = v[i].y; d[2] = v[i].z; d[3] = v[i].w; }
;     asm volatile("s_waitcnt lgkmcnt(0)" ::: "memory");
;     const int c = lane & 7;
;     const int rowbase = mode == 0 ? n0 : (((n0 >> 7) << 8) + (n0 & 127) + (mode == 2 ? 128 : 0));
; #pragma unroll
;     for (int j = 0; j < 8; ++j) { const int n = (lane >> 3) + 8 * j; const LAS float* s = scr + (8 * c) * 65 + n;
;         v4u o; o.x = pk2(s[0 * 65], s[1 * 65]); o.y = pk2(s[2 * 65], s[3 * 65]); o.z = pk2(s[4 * 65], s[5 * 65]); o.w = pk2(s[6 * 65], s[7 * 65]);
;         *(v4u*)(WT + (size_t)(rowbase + n) * K + k0 + 8 * c) = o; }
.LBB0_36:
	s_lshl_b32 s24, s55, 6
	s_lshl_b32 s25, s55, 7
	s_and_b32 s24, s24, 64
	s_waitcnt vmcnt(15)
	ds_write2_b32 v73, v6, v7 offset1:1
	ds_write2_b32 v73, v8, v9 offset0:2 offset1:3
	s_waitcnt vmcnt(14)
	ds_write2_b32 v83, v2, v3 offset1:1
	ds_write2_b32 v84, v4, v5 offset1:1
	s_waitcnt vmcnt(13)
	ds_write2_b32 v85, v14, v15 offset1:1
	ds_write2_b32 v86, v16, v17 offset1:1
	s_waitcnt vmcnt(12)
	ds_write2_b32 v87, v10, v11 offset1:1
	ds_write2_b32 v88, v12, v13 offset1:1
	s_waitcnt vmcnt(11)
	ds_write2_b32 v89, v22, v23 offset1:1
	ds_write2_b32 v90, v24, v25 offset1:1
	s_waitcnt vmcnt(10)
	ds_write2_b32 v91, v18, v19 offset1:1
	ds_write2_b32 v92, v20, v21 offset1:1
	s_waitcnt vmcnt(9)
	ds_write2_b32 v93, v30, v31 offset1:1
	ds_write2_b32 v94, v32, v33 offset1:1
	s_waitcnt vmcnt(8)
	ds_write2_b32 v95, v26, v27 offset1:1
	ds_write2_b32 v96, v28, v29 offset1:1
	s_waitcnt vmcnt(7)
	ds_write2_b32 v97, v38, v39 offset1:1
	ds_write2_b32 v98, v40, v41 offset1:1
	s_waitcnt vmcnt(6)
	ds_write2_b32 v99, v34, v35 offset1:1
	ds_write2_b32 v100, v36, v37 offset1:1
	s_waitcnt vmcnt(5)
	ds_write2_b32 v101, v46, v47 offset1:1
	ds_write2_b32 v102, v48, v49 offset1:1
	s_waitcnt vmcnt(4)
	ds_write2_b32 v103, v42, v43 offset1:1
	ds_write2_b32 v104, v44, v45 offset1:1
	s_waitcnt vmcnt(3)
	ds_write2_b32 v105, v54, v55 offset1:1
	ds_write2_b32 v106, v56, v57 offset1:1
	s_waitcnt vmcnt(2)
	ds_write2_b32 v107, v50, v51 offset1:1
	ds_write2_b32 v108, v52, v53 offset1:1
	s_waitcnt vmcnt(1)
	ds_write2_b32 v109, v62, v63 offset1:1
	ds_write2_b32 v110, v64, v65 offset1:1
	s_waitcnt vmcnt(0)
	ds_write2_b32 v111, v58, v59 offset1:1
	ds_write2_b32 v112, v60, v61 offset1:1
	s_or_b32 s24, s24, s25
	s_and_b32 s21, 0xffff, s21
	s_waitcnt lgkmcnt(0)
	s_bitset1_b32 s24, 7
	s_lshl_b32 s21, s21, 1
	ds_read2_b32 v[150:151], v75 offset1:65
	ds_read2_b32 v[152:153], v75 offset0:130 offset1:195
	ds_read2_b32 v[154:155], v113 offset0:4 offset1:69
	ds_read2_b32 v[156:157], v113 offset0:134 offset1:199
	ds_read2_b32 v[158:159], v75 offset0:8 offset1:73
	ds_read2_b32 v[160:161], v75 offset0:138 offset1:203
	ds_read2_b32 v[162:163], v113 offset0:12 offset1:77
	ds_read2_b32 v[164:165], v113 offset0:142 offset1:207
	ds_read2_b32 v[166:167], v75 offset0:16 offset1:81
	ds_read2_b32 v[168:169], v75 offset0:146 offset1:211
	ds_read2_b32 v[170:171], v113 offset0:20 offset1:85
	ds_read2_b32 v[172:173], v113 offset0:150 offset1:215
	ds_read2_b32 v[174:175], v75 offset0:24 offset1:89
	ds_read2_b32 v[176:177], v75 offset0:154 offset1:219
	ds_read2_b32 v[178:179], v113 offset0:28 offset1:93
	ds_read2_b32 v[180:181], v113 offset0:158 offset1:223
	ds_read2_b32 v[182:183], v75 offset0:32 offset1:97
	ds_read2_b32 v[184:185], v75 offset0:162 offset1:227
	ds_read2_b32 v[186:187], v113 offset0:36 offset1:101
	ds_read2_b32 v[188:189], v113 offset0:166 offset1:231
	ds_read2_b32 v[190:191], v75 offset0:40 offset1:105
	ds_read2_b32 v[192:193], v75 offset0:170 offset1:235
	ds_read2_b32 v[194:195], v113 offset0:44 offset1:109
	ds_read2_b32 v[196:197], v113 offset0:174 offset1:239
	ds_read2_b32 v[198:199], v75 offset0:48 offset1:113
	ds_read2_b32 v[200:201], v75 offset0:178 offset1:243
	ds_read2_b32 v[202:203], v113 offset0:52 offset1:117
	ds_read2_b32 v[204:205], v113 offset0:182 offset1:247
	ds_read2_b32 v[206:207], v75 offset0:56 offset1:121
	ds_read2_b32 v[208:209], v75 offset0:186 offset1:251
	ds_read2_b32 v[210:211], v113 offset0:60 offset1:125
	ds_read2_b32 v[212:213], v113 offset0:190 offset1:255
	s_add_u32 s56, s52, s21
	s_waitcnt lgkmcnt(15)
	v_cvt_pk_bf16_f32 v214, v150, v151
	s_addc_u32 s57, s53, 0
	v_mov_b32_e32 v69, v67
	v_or_b32_e32 v10, s24, v74
	s_waitcnt lgkmcnt(15)
; #define LAS __attribute__((address_space(3)))
; __device__ __forceinline__ unsigned pk2(float lo, float hi) { return pg8::cvt_pk_bf16(lo, hi); }
; __device__ __forceinline__ void p0_transpose_item(const float* __restrict__ W, const float* __restrict__ gain, int K, int N, bf16* __restrict__ WT, int mode, LAS float* scr, int item, int lane) {
;     ...
;     for (int j = 0; j < 8; ++j) { const int n = (lane >> 3) + 8 * j; const LAS float* s = scr + (8 * c) * 65 + n;
;         v4u o; o.x = pk2(s[0 * 65], s[1 * 65]); o.y = pk2(s[2 * 65], s[3 * 65]); o.z = pk2(s[4 * 65], s[5 * 65]); o.w = pk2(s[6 * 65], s[7 * 65]);
;         *(v4u*)(WT + (size_t)(rowbase + n) * K + k0 + 8 * c) = o; }
;     asm volatile("s_waitcnt lgkmcnt(0)" ::: "memory");
	v_cvt_pk_bf16_f32 v215, v152, v153
	v_lshl_add_u64 v[8:9], s[56:57], 0, v[68:69]
	v_lshlrev_b32_e32 v10, 12, v10
	v_mov_b32_e32 v11, v67
	s_waitcnt lgkmcnt(15)
	v_cvt_pk_bf16_f32 v216, v154, v155
	s_waitcnt lgkmcnt(15)
	v_cvt_pk_bf16_f32 v217, v156, v157
	v_lshl_add_u64 v[10:11], v[8:9], 0, v[10:11]
	global_store_dwordx4 v[10:11], v[214:217], off
	v_or_b32_e32 v10, s24, v76
	v_lshlrev_b32_e32 v10, 12, v10
	s_waitcnt lgkmcnt(15)
	v_cvt_pk_bf16_f32 v218, v158, v159
	s_waitcnt lgkmcnt(15)
	v_cvt_pk_bf16_f32 v219, v160, v161
	v_mov_b32_e32 v11, v67
	s_waitcnt lgkmcnt(15)
	v_cvt_pk_bf16_f32 v220, v162, v163
	s_waitcnt lgkmcnt(15)
	v_cvt_pk_bf16_f32 v221, v164, v165
	v_lshl_add_u64 v[10:11], v[8:9], 0, v[10:11]
	global_store_dwordx4 v[10:11], v[218:221], off
	v_or_b32_e32 v10, s24, v77
	v_lshlrev_b32_e32 v10, 12, v10
	s_waitcnt lgkmcnt(15)
	v_cvt_pk_bf16_f32 v222, v166, v167
	s_waitcnt lgkmcnt(15)
	v_cvt_pk_bf16_f32 v223, v168, v169
	v_mov_b32_e32 v11, v67
	s_waitcnt lgkmcnt(15)
	v_cvt_pk_bf16_f32 v224, v170, v171
	s_waitcnt lgkmcnt(15)
	v_cvt_pk_bf16_f32 v225, v172, v173
	v_lshl_add_u64 v[10:11], v[8:9], 0, v[10:11]
	global_store_dwordx4 v[10:11], v[222:225], off
	v_or_b32_e32 v10, s24, v78
	v_lshlrev_b32_e32 v10, 12, v10
	s_waitcnt lgkmcnt(15)
	v_cvt_pk_bf16_f32 v226, v174, v175
	s_waitcnt lgkmcnt(15)
	v_cvt_pk_bf16_f32 v227, v176, v177
	v_mov_b32_e32 v11, v67
	s_waitcnt lgkmcnt(15)
	v_cvt_pk_bf16_f32 v228, v178, v179
	s_waitcnt lgkmcnt(15)
	v_cvt_pk_bf16_f32 v229, v180, v181
	v_lshl_add_u64 v[10:11], v[8:9], 0, v[10:11]
	global_store_dwordx4 v[10:11], v[226:229], off
	v_or_b32_e32 v10, s24, v79
	v_lshlrev_b32_e32 v10, 12, v10
	s_waitcnt lgkmcnt(15)
	v_cvt_pk_bf16_f32 v230, v182, v183
	s_waitcnt lgkmcnt(14)
	v_cvt_pk_bf16_f32 v231, v184, v185
	v_mov_b32_e32 v11, v67
	s_waitcnt lgkmcnt(13)
	v_cvt_pk_bf16_f32 v232, v186, v187
	s_waitcnt lgkmcnt(12)
	v_cvt_pk_bf16_f32 v233, v188, v189
	v_lshl_add_u64 v[10:11], v[8:9], 0, v[10:11]
	global_store_dwordx4 v[10:11], v[230:233], off
	v_or_b32_e32 v10, s24, v80
	v_mov_b32_e32 v11, v67
	s_waitcnt lgkmcnt(11)
	v_cvt_pk_bf16_f32 v234, v190, v191
	s_waitcnt lgkmcnt(10)
	v_cvt_pk_bf16_f32 v235, v192, v193
	v_lshlrev_b32_e32 v10, 12, v10
	s_waitcnt lgkmcnt(9)
	v_cvt_pk_bf16_f32 v236, v194, v195
	s_waitcnt lgkmcnt(8)
	v_cvt_pk_bf16_f32 v237, v196, v197
	v_lshl_add_u64 v[10:11], v[8:9], 0, v[10:11]
	global_store_dwordx4 v[10:11], v[234:237], off
	v_or_b32_e32 v10, s24, v81
	v_mov_b32_e32 v11, v67
	s_waitcnt lgkmcnt(7)
	v_cvt_pk_bf16_f32 v238, v198, v199
	s_waitcnt lgkmcnt(6)
	v_cvt_pk_bf16_f32 v239, v200, v201
	v_lshlrev_b32_e32 v10, 12, v10
	s_waitcnt lgkmcnt(5)
	v_cvt_pk_bf16_f32 v240, v202, v203
	s_waitcnt lgkmcnt(4)
	v_cvt_pk_bf16_f32 v241, v204, v205
	v_lshl_add_u64 v[10:11], v[8:9], 0, v[10:11]
	global_store_dwordx4 v[10:11], v[238:241], off
	v_mov_b32_e32 v11, v67
	v_readlane_b32 s76, v254, 21
	s_waitcnt lgkmcnt(3)
	v_cvt_pk_bf16_f32 v242, v206, v207
	s_waitcnt lgkmcnt(2)
	v_cvt_pk_bf16_f32 v243, v208, v209
	s_waitcnt lgkmcnt(1)
	v_cvt_pk_bf16_f32 v244, v210, v211
	v_or_b32_e32 v5, s24, v82
	v_lshlrev_b32_e32 v10, 12, v5
	s_waitcnt lgkmcnt(0)
	v_cvt_pk_bf16_f32 v245, v212, v213
	v_lshl_add_u64 v[6:7], v[8:9], 0, v[10:11]
	global_store_dwordx4 v[6:7], v[242:245], off
	s_waitcnt lgkmcnt(0)
	v_readlane_b32 s77, v254, 22
	v_readlane_b32 s78, v254, 23
	v_readlane_b32 s79, v254, 24
	v_readlane_b32 s80, v254, 25
	v_readlane_b32 s81, v254, 26
	v_readlane_b32 s82, v254, 27
	v_readlane_b32 s83, v254, 28
	v_readlane_b32 s84, v254, 29
	v_readlane_b32 s85, v254, 30
	v_readlane_b32 s86, v254, 31
	v_readlane_b32 s87, v254, 32
	v_readlane_b32 s88, v254, 33
	v_readlane_b32 s89, v254, 34
	v_readlane_b32 s90, v254, 35
	v_readlane_b32 s91, v254, 36
